# v13: stick-breaking unit with 8-slot ring and per-wave diagonal-aligned tiles (all waves active from step 0) + three mid-size heavy units per (b,h) moved to the light queues
# speedup vs baseline: 1.0725x; 1.0183x over previous
; __global__ void __launch_bounds__(512) fwd_megakernel(Args a) {
;     ...
;             if (tq0_ == 0) { int slot = -1;
;                 while (tries < 8) { int len = (myq < 4) ? 64 : 192;
;     ...
;                     if (rep) len = 64;
;     ...
;                     if (rep) { if (myq < 4) len = 0; }
;     ...
;  const int idx = (int)atomicAdd(barw + BAR_QCTR + 64 * myq, 1u);
;     ...
;                     if (rep && myq >= 4 && idx < 64) continue;
;     ...
;                     if (idx < len) { slot = (myq << 16) | idx; break; } myq = (myq + 1) & 7; ++tries; }
;                 qslot[0] = slot; }
.LBB0_350:
	v_cmp_gt_i32_e32 vcc, 8, v239
	s_or_b64 s[24:25], s[24:25], exec
	s_and_saveexec_b64 s[26:27], vcc
	s_cbranch_execz .LBB0_349
	v_readlane_b32 s12, v254, 56
	v_lshlrev_b32_e32 v0, 6, v233
	v_readlane_b32 s13, v254, 57
	v_cmp_gt_i32_e32 vcc, 4, v233
	s_nop 0
	v_lshl_add_u64 v[4:5], v[0:1], 2, s[12:13]
	global_atomic_add v0, v[4:5], v231, off sc0
	v_and_b32_e32 v3, 1, v233
	v_lshlrev_b32_e32 v3, 6, v3
	v_add_u32_e32 v3, 0xa3, v3
	v_cndmask_b32_e64 v3, v3, 61, vcc
	s_waitcnt vmcnt(0)
	v_cmp_ge_i32_e32 vcc, v0, v3
	s_and_saveexec_b64 s[12:13], vcc
	s_xor_b64 s[36:37], exec, s[12:13]
	v_add_u32_e32 v4, 1, v233
	v_and_b32_e32 v233, 7, v4
	v_add_u32_e32 v239, 1, v239
	s_andn2_saveexec_b64 s[36:37], s[36:37]
	s_cbranch_execz .LBB0_348
	v_lshl_or_b32 v2, v233, 16, v0
	s_branch .LBB0_348

; __global__ void __launch_bounds__(512) fwd_megakernel(Args a) {
;     ...
;             __syncthreads();
;             const int slot = qslot[0];
;             if (slot < 0) break;
;             const int q = slot >> 16, idx = slot & 0xffff;
;             int ub, uh, uq; bool isdf = true;
;             if (q < 4) { ub = q >> 1; uh = 3 - (q & 1); uq = 63 - idx; }
;             else { const int y = q - 4;
;                 if (idx < 64) { ub = y >> 1; uh = 1 - (y & 1); uq = 63 - idx; }
;                 else { const int v = idx - 64; const int bh = 4 * y + (v & 3); ub = bh >> 3; uh = bh & 7; uq = 31 - (v >> 2); isdf = false; } }
.LBB0_356:
	s_or_b64 exec, exec, s[0:1]
	s_add_i32 s0, s4, 0
	v_mov_b32_e32 v0, s0
	s_waitcnt lgkmcnt(0)
	s_barrier
	ds_read_b32 v0, v0
	s_waitcnt lgkmcnt(0)
	v_cmp_gt_i32_e32 vcc, 0, v0
	v_readfirstlane_b32 s4, v0
	s_cbranch_vccnz .LBB0_370
	s_and_b32 s5, s4, 0xffff
	s_cmp_gt_u32 s4, 0x3ffff
	s_mov_b64 s[6:7], -1
	s_cbranch_scc0 .LBB0_367
	s_lshr_b32 s12, s4, 16
	s_add_i32 s12, s12, -4
	s_cmp_lt_u32 s5, 3
	s_cbranch_scc0 .Lmv_not
	s_lshr_b32 s14, s12, 1
	s_and_b32 s16, s12, 1
	s_sub_i32 s16, 3, s16
	s_sub_i32 s15, 31, s5
	s_mov_b64 s[0:1], -1
	s_branch .LBB0_369
.Lmv_not:
	s_add_i32 s5, s5, -3
	s_cmp_lt_u32 s5, 64
	s_cselect_b64 s[0:1], -1, 0
	s_cmp_gt_u32 s5, 63
	s_cbranch_scc0 .LBB0_360
	s_sub_i32 s6, s5, 64
	s_cmp_lt_u32 s6, 0x80
	s_cbranch_scc1 .Lsbq_own
	s_add_i32 s12, s12, -1
	s_add_i32 s6, s6, -32
.Lsbq_own:
	s_lshl_b32 s7, s12, 2
	s_and_b32 s13, s5, 3
	s_and_b32 s7, s7, 4
	s_lshr_b32 s6, s6, 2
	s_or_b32 s16, s7, s13
	s_sub_i32 s15, 31, s6
	s_mov_b64 s[6:7], 0

; #define LAS __attribute__((address_space(3)))
; #define WAIT_BAR0() asm volatile("s_waitcnt vmcnt(0) lgkmcnt(0)\n\ts_barrier" ::: "memory")
; #define SB_DMA(T, st) do { const unsigned base_ = lds0 + (st) * 16384 + wid * 1024; glds16(ksrc + (size_t)(T) * 64 * 512, RFL(base_)); glds16(vsrc + (size_t)(T) * 4096, RFL(base_ + 8192)); } while (0)
; DI void sb_unit(LAS char* lds, int b, int h, int qb, const bf16_t* __restrict__ Q, const bf16_t* __restrict__ K, const bf16_t* __restrict__ VT, const bf16_t* __restrict__ G, bf16_t* __restrict__ MIX) {
;     ...
;     const int tid = tid_, lane = tid & 63, r32 = lane & 31, hi = lane >> 5; const int wid = __builtin_amdgcn_readfirstlane(tid >> 6);
;     const int q0 = qb * 256, qw0 = q0 + 32 * wid, tq = qw0 + r32;
;     volatile LAS int* flags = (volatile LAS int*)(lds + MISC_OFF);
;     const unsigned lds0 = (unsigned)(uintptr_t)lds;
;     bf16x8 qf[4];
; #pragma unroll
;     for (int d0 = 0; d0 < 4; ++d0) qf[d0] = *(const bf16x8*)(Q + (size_t)(b * SEQ + tq) * 512 + h * 64 + d0 * 16 + hi * 8);
;     bf16x8 tp0, tp1, ones;
; #pragma unroll
;     for (int j = 0; j < 8; ++j) { const int kvk = 8 * (j >> 2) + 4 * hi + (j & 3); tp0[j] = (kvk > r32) ? (short)0x3F80 : (short)0; tp1[j] = (16 + kvk > r32) ? (short)0x3F80 : (short)0; ones[j] = (short)0x3F80; }
;     const int drow = 8 * wid + (lane >> 3), dch = (lane & 7) ^ ((drow >> 1) & 7);
;     const bf16_t* ksrc = K + (size_t)(b * SEQ + drow) * 512 + h * 64 + dch * 8;
;     const bf16_t* vsrc = VT + (size_t)(b * 8 + h) * (SEQ * 64) + drow * 64 + dch * 8;
;     ...
;     f32x16 o0 = splat16(0.f), o1 = splat16(0.f); float carry = 0.f; int done = 0;
;     const int nt = (q0 + 256) / 64;
;     WAIT_BAR0();
;     SB_DMA(nt - 1, 0);
.LBB0_363:
	s_andn2_b64 vcc, exec, s[0:1]
	s_mov_b64 s[0:1], -1
	s_cbranch_vccz .LBB0_369
	v_mov_b32_e32 v35, v236
	s_lshl_b32 s4, s15, 8
	v_readfirstlane_b32 s0, v35
	s_ashr_i32 s27, s0, 6
	s_lshl_b32 s24, s27, 5
	v_bfe_u32 v0, v35, 3, 3
	v_and_b32_e32 v100, 31, v35
	s_add_i32 s24, s24, s4
	s_lshl_b32 s0, s14, 13
	v_lshl_or_b32 v6, s27, 3, v0
	v_or_b32_e32 v101, s24, v100
	v_add_u32_e32 v4, s0, v6
	v_add_u32_e32 v92, s0, v101
	v_ashrrev_i32_e32 v5, 31, v4
	v_readlane_b32 s0, v253, 4
	v_lshlrev_b64 v[4:5], 10, v[4:5]
	v_readlane_b32 s1, v253, 5
	v_lshrrev_b32_e32 v0, 1, v6
	s_lshl_b32 s98, s16, 7
	v_lshl_add_u64 v[4:5], s[0:1], 0, v[4:5]
	s_lshl_b32 s0, s14, 3
	v_xor_b32_e32 v0, v0, v35
	v_lshl_add_u64 v[4:5], v[4:5], 0, s[98:99]
	s_add_i32 s98, s0, s16
	s_lshl_b32 s23, s16, 6
	v_lshlrev_b32_e32 v0, 4, v0
	s_lshl_b64 s[0:1], s[98:99], 20
	v_readlane_b32 s6, v253, 14
	v_and_b32_e32 v0, 0x70, v0
	v_readlane_b32 s7, v253, 15
	s_add_u32 s0, s6, s0
	v_lshl_add_u64 v[96:97], v[4:5], 0, v[0:1]
	s_addc_u32 s1, s7, s1
	v_lshlrev_b32_e32 v4, 6, v6
	s_addk_i32 s4, 0x100
	v_ashrrev_i32_e32 v5, 31, v4
	s_ashr_i32 s38, s4, 6
	v_lshl_add_u64 v[4:5], v[4:5], 1, s[0:1]
	s_add_i32 s0, s38, -1
	s_ashr_i32 s1, s0, 31
	s_waitcnt lgkmcnt(0)
	s_barrier
	s_lshl_b32 s25, s27, 10
	s_lshl_b64 s[4:5], s[0:1], 16
	v_lshl_add_u64 v[98:99], v[4:5], 0, v[0:1]
	v_lshl_add_u64 v[4:5], v[96:97], 0, s[4:5]
	s_add_i32 s25, s25, 0
	s_and_b32 s46, s0, 7
	s_lshl_b32 s46, s46, 14
	s_add_i32 s46, s46, s25
	s_mov_b32 s4, m0
	s_mov_b32 m0, s46
	s_nop 0
	global_load_lds_dwordx4 v[4:5], off
	s_mov_b32 m0, s4
	s_lshl_b64 s[4:5], s[0:1], 13
	v_bfe_u32 v2, v35, 5, 1
	v_lshl_add_u64 v[4:5], v[98:99], 0, s[4:5]
	s_add_i32 s1, s46, 0x2000
	s_mov_b32 s4, m0
	s_mov_b32 m0, s1
	s_nop 0
	global_load_lds_dwordx4 v[4:5], off
	s_mov_b32 m0, s4
	s_add_i32 s47, s0, -1
	s_and_b32 s48, s47, 7
	s_lshl_b32 s48, s48, 14
	s_add_i32 s48, s48, s25
	s_mov_b32 s50, s47
	s_mov_b32 s51, 0
	s_lshl_b64 s[50:51], s[50:51], 16
	v_lshl_add_u64 v[4:5], v[96:97], 0, s[50:51]
	s_mov_b32 m0, s48
	s_nop 0
	global_load_lds_dwordx4 v[4:5], off
	s_mov_b32 s50, s47
	s_mov_b32 s51, 0
	s_lshl_b64 s[50:51], s[50:51], 13
	v_lshl_add_u64 v[4:5], v[98:99], 0, s[50:51]
	s_add_i32 s48, s48, 0x2000
	s_mov_b32 m0, s48
	s_nop 0
	global_load_lds_dwordx4 v[4:5], off
	s_add_i32 s47, s0, -2
	s_and_b32 s48, s47, 7
	s_lshl_b32 s48, s48, 14
	s_add_i32 s48, s48, s25
	s_mov_b32 s50, s47
	s_mov_b32 s51, 0
	s_lshl_b64 s[50:51], s[50:51], 16
	v_lshl_add_u64 v[4:5], v[96:97], 0, s[50:51]
	s_mov_b32 m0, s48
	s_nop 0
	global_load_lds_dwordx4 v[4:5], off
	s_mov_b32 s50, s47
	s_mov_b32 s51, 0
	s_lshl_b64 s[50:51], s[50:51], 13
	v_lshl_add_u64 v[4:5], v[98:99], 0, s[50:51]
	s_add_i32 s48, s48, 0x2000
	s_mov_b32 m0, s48
	s_nop 0
	global_load_lds_dwordx4 v[4:5], off
	s_add_i32 s47, s0, -3
	s_and_b32 s48, s47, 7
	s_lshl_b32 s48, s48, 14
	s_add_i32 s48, s48, s25
	s_mov_b32 s50, s47
	s_mov_b32 s51, 0
	s_lshl_b64 s[50:51], s[50:51], 16
	v_lshl_add_u64 v[4:5], v[96:97], 0, s[50:51]
	s_mov_b32 m0, s48
	s_nop 0
	global_load_lds_dwordx4 v[4:5], off
	s_mov_b32 s50, s47
	s_mov_b32 s51, 0
	s_lshl_b64 s[50:51], s[50:51], 13
	v_lshl_add_u64 v[4:5], v[98:99], 0, s[50:51]
	s_add_i32 s48, s48, 0x2000
	s_mov_b32 m0, s48
	s_nop 0
	global_load_lds_dwordx4 v[4:5], off
	v_ashrrev_i32_e32 v93, 31, v92
	v_lshlrev_b32_e32 v3, 3, v2
	v_lshlrev_b64 v[94:95], 10, v[92:93]
	s_cmp_lt_i32 s38, 1
	v_lshlrev_b32_e32 v0, 1, v3
	s_cbranch_scc1 .LBB0_371
	v_readlane_b32 s4, v253, 2
	v_readlane_b32 s5, v253, 3
	s_lshl_b32 s98, s23, 1
	v_lshlrev_b32_e32 v102, 2, v2
	v_lshl_add_u64 v[4:5], s[4:5], 0, v[94:95]
	v_lshl_add_u64 v[4:5], v[4:5], 0, s[98:99]
	v_lshl_add_u64 v[4:5], v[4:5], 0, v[0:1]
	global_load_dwordx4 v[68:71], v[4:5], off
	global_load_dwordx4 v[72:75], v[4:5], off offset:32
	global_load_dwordx4 v[76:79], v[4:5], off offset:64
	global_load_dwordx4 v[80:83], v[4:5], off offset:96
	v_or_b32_e32 v3, 16, v102
	v_cmp_gt_u32_e32 vcc, v3, v100
	v_mov_b32_e32 v15, 0x3f80
	v_or_b32_e32 v5, 17, v102
	v_cndmask_b32_e32 v3, 0, v15, vcc
	v_or_b32_e32 v4, 18, v102
	v_cmp_gt_u32_e32 vcc, v5, v100
	v_or_b32_e32 v7, 19, v102
	v_or_b32_e32 v6, 24, v102
	v_cndmask_b32_e32 v5, 0, v15, vcc
	v_cmp_gt_u32_e32 vcc, v4, v100
	v_or_b32_e32 v8, 26, v102
	v_or_b32_e32 v9, 25, v102
	v_cndmask_b32_e32 v4, 0, v15, vcc
	v_cmp_gt_u32_e32 vcc, v7, v100
	v_or_b32_e32 v10, 27, v102
	s_mov_b32 s1, 0x5040100
	v_cndmask_b32_e32 v7, 0, v15, vcc
	v_cmp_gt_u32_e32 vcc, v6, v100
	v_or_b32_e32 v12, 10, v102
	v_or_b32_e32 v11, 11, v102
	v_cndmask_b32_e32 v6, 0, v15, vcc
	v_cmp_gt_u32_e32 vcc, v8, v100
	v_perm_b32 v88, v5, v3, s1
	s_add_i32 s98, s38, -2
	v_cndmask_b32_e32 v8, 0, v15, vcc
	v_cmp_gt_u32_e32 vcc, v9, v100
	s_waitcnt vmcnt(0) lgkmcnt(0)
	s_barrier
; #define LAS __attribute__((address_space(3)))
; #define MFMA32(a, b, c) __builtin_amdgcn_mfma_f32_32x32x16_bf16((a), (b), (c), 0, 0, 0)
; #define WAIT_BAR0() asm volatile("s_waitcnt vmcnt(0) lgkmcnt(0)\n\ts_barrier" ::: "memory")
; #define SB_DMA(T, st) do { const unsigned base_ = lds0 + (st) * 16384 + wid * 1024; glds16(ksrc + (size_t)(T) * 64 * 512, RFL(base_)); glds16(vsrc + (size_t)(T) * 4096, RFL(base_ + 8192)); } while (0)
; DI void sb_unit(LAS char* lds, int b, int h, int qb, const bf16_t* __restrict__ Q, const bf16_t* __restrict__ K, const bf16_t* __restrict__ VT, const bf16_t* __restrict__ G, bf16_t* __restrict__ MIX) {
;     ...
;     for (int j = 0; j < 8; ++j) { const int kvk = 8 * (j >> 2) + 4 * hi + (j & 3); tp0[j] = (kvk > r32) ? (short)0x3F80 : (short)0; tp1[j] = (16 + kvk > r32) ? (short)0x3F80 : (short)0; ones[j] = (short)0x3F80; }
;     const int drow = 8 * wid + (lane >> 3), dch = (lane & 7) ^ ((drow >> 1) & 7);
;     const bf16_t* ksrc = K + (size_t)(b * SEQ + drow) * 512 + h * 64 + dch * 8;
;     const bf16_t* vsrc = VT + (size_t)(b * 8 + h) * (SEQ * 64) + drow * 64 + dch * 8;
;     ...
;     f32x16 o0 = splat16(0.f), o1 = splat16(0.f); float carry = 0.f; int done = 0;
;     const int nt = (q0 + 256) / 64;
;     WAIT_BAR0();
;     SB_DMA(nt - 1, 0);
;     for (int T = nt - 1, it = 0; T >= 0; --T, ++it) {
;         WAIT_BAR0();
;         if (it > 0) { volatile LAS int* fl = flags + ((it & 1) ^ 1) * 8; const int all = fl[0] & fl[1] & fl[2] & fl[3] & fl[4] & fl[5] & fl[6] & fl[7]; if (all) break; }
;         if (T > 0) SB_DMA(T - 1, (it + 1) & 1);
;         const LAS char* Kt = lds + (it & 1) * 16384; const LAS char* Vt = Kt + 8192;
;         const int kv0 = 64 * T;
;         if (kv0 < qw0 + 31 && !done) {
;             f32x16 p0 = splat16(0.f), p1 = splat16(0.f);
; #pragma unroll
;             for (int d0 = 0; d0 < 4; ++d0) { const bf16x8 k0 = ldsv(Kt + off128(r32, 2 * d0 + hi)), k1 = ldsv(Kt + off128(32 + r32, 2 * d0 + hi)); p0 = MFMA32(k0, qf[d0], p0); p1 = MFMA32(k1, qf[d0], p1); }
	s_lshl_b64 s[4:5], s[98:99], 16
	v_perm_b32 v89, v7, v4, s1
	v_cndmask_b32_e32 v9, 0, v15, vcc
	v_cmp_gt_u32_e32 vcc, v10, v100
	v_perm_b32 v90, v9, v6, s1
	s_or_b32 s26, s24, 31
	v_cndmask_b32_e32 v10, 0, v15, vcc
	v_cmp_gt_u32_e32 vcc, v102, v100
	v_perm_b32 v91, v10, v8, s1
	v_lshlrev_b32_e32 v103, 7, v100
	v_cndmask_b32_e32 v13, 0, v15, vcc
	v_cmp_lt_u32_e32 vcc, v102, v100
	s_nop 1
	v_cndmask_b32_e64 v14, v15, 0, vcc
	v_perm_b32 v84, v14, v13, s1
	v_or_b32_e32 v14, 2, v102
	v_or_b32_e32 v13, 3, v102
	v_cmp_gt_u32_e32 vcc, v14, v100
	s_nop 1
	v_cndmask_b32_e32 v14, 0, v15, vcc
	v_cmp_gt_u32_e32 vcc, v13, v100
	s_nop 1
	v_cndmask_b32_e32 v13, 0, v15, vcc
	v_perm_b32 v85, v13, v14, s1
	v_or_b32_e32 v14, 8, v102
	v_or_b32_e32 v13, 9, v102
	v_cmp_gt_u32_e32 vcc, v14, v100
	s_nop 1
	v_cndmask_b32_e32 v14, 0, v15, vcc
	v_cmp_gt_u32_e32 vcc, v13, v100
	s_nop 1
	v_cndmask_b32_e32 v13, 0, v15, vcc
	v_cmp_gt_u32_e32 vcc, v12, v100
	v_perm_b32 v86, v13, v14, s1
	s_nop 0
	v_cndmask_b32_e32 v12, 0, v15, vcc
	v_cmp_gt_u32_e32 vcc, v11, v100
	s_nop 1
	v_cndmask_b32_e32 v11, 0, v15, vcc
	v_perm_b32 v87, v11, v12, s1
	v_lshrrev_b32_e32 v11, 1, v35
	v_bfe_u32 v12, v35, 1, 3
	v_bitop3_b32 v3, v11, v2, 7 bitop3:0x6c
	v_lshlrev_b32_e32 v104, 4, v3
	v_bitop3_b32 v3, v2, v12, 2 bitop3:0x36
	v_lshlrev_b32_e32 v105, 4, v3
	v_bitop3_b32 v3, v2, v12, 4 bitop3:0x36
	v_bitop3_b32 v2, v2, v12, 6 bitop3:0x36
	v_lshlrev_b32_e32 v106, 4, v3
	v_lshlrev_b32_e32 v107, 4, v2
	v_lshl_add_u64 v[2:3], v[96:97], 0, s[4:5]
	s_add_i32 s1, s25, 0x4000
	s_mov_b32 s4, m0
	s_mov_b32 m0, s1
	s_nop 0
	s_nop 0
	s_mov_b32 m0, s4
	s_lshl_b64 s[4:5], s[98:99], 13
	v_lshl_add_u64 v[2:3], v[98:99], 0, s[4:5]
	s_add_i32 s1, s25, 0x6000
	s_lshl_b32 s4, s0, 6
	s_mov_b32 s0, m0
	s_mov_b32 m0, s1
	s_nop 0
	s_nop 0
	s_mov_b32 m0, s0
	s_nop 0
	s_branch .LBB0_413
	v_add_u32_e32 v34, 0, v103
	v_add_u32_e32 v6, v34, v104
	ds_read_b128 v[2:5], v6
	ds_read_b128 v[6:9], v6 offset:4096
	v_add_u32_e32 v40, v34, v105
	ds_read_b128 v[36:39], v40
	ds_read_b128 v[40:43], v40 offset:4096
	s_or_b32 s0, s4, 63
	s_waitcnt lgkmcnt(3)
	v_mfma_f32_32x32x16_bf16 v[18:33], v[2:5], v[68:71], 0
	s_cmp_lt_i32 s0, s24
	s_cselect_b64 s[0:1], -1, 0
	s_waitcnt lgkmcnt(2)
	v_mfma_f32_32x32x16_bf16 v[2:17], v[6:9], v[68:71], 0
	s_waitcnt lgkmcnt(1)
	v_mfma_f32_32x32x16_bf16 v[18:33], v[36:39], v[72:75], v[18:33]
	s_waitcnt lgkmcnt(0)
	v_mfma_f32_32x32x16_bf16 v[2:17], v[40:43], v[72:75], v[2:17]
	v_add_u32_e32 v40, v34, v106
	ds_read_b128 v[36:39], v40
	ds_read_b128 v[40:43], v40 offset:4096
	v_add_u32_e32 v34, v34, v107
	s_waitcnt lgkmcnt(1)
	v_mfma_f32_32x32x16_bf16 v[18:33], v[36:39], v[76:79], v[18:33]
	s_waitcnt lgkmcnt(0)
	v_mfma_f32_32x32x16_bf16 v[2:17], v[40:43], v[76:79], v[2:17]
	ds_read_b128 v[36:39], v34
	ds_read_b128 v[40:43], v34 offset:4096
	s_waitcnt lgkmcnt(1)
	v_mfma_f32_32x32x16_bf16 v[18:33], v[36:39], v[80:83], v[18:33]
	s_waitcnt lgkmcnt(0)
	v_mfma_f32_32x32x16_bf16 v[2:17], v[40:43], v[80:83], v[2:17]
	s_nop 9
	v_exp_f32_e32 v34, v18
	v_or_b32_e32 v41, s4, v102
	v_cmp_lt_f32_e32 vcc, s22, v18
	v_or_b32_e32 v37, 32, v41
	v_add_f32_e32 v34, 1.0, v34
	v_log_f32_e32 v34, v34
	v_or_b32_e32 v61, 24, v41
	v_readlane_b32 s4, v254, 48
	v_readlane_b32 s6, v254, 50
	v_cndmask_b32_e32 v36, v34, v18, vcc
	v_cmp_lt_i32_e32 vcc, v41, v101
	s_or_b64 vcc, s[0:1], vcc
	v_sub_f32_e32 v18, v18, v36
	v_cndmask_b32_e64 v34, 0, -v36, vcc
	v_cndmask_b32_e32 v36, v237, v18, vcc
	v_exp_f32_e32 v18, v2
	v_cmp_lt_f32_e32 vcc, s22, v2
	v_readlane_b32 s7, v254, 51
	v_readlane_b32 s5, v254, 49
	v_add_f32_e32 v18, 1.0, v18
	v_log_f32_e32 v18, v18
	s_mov_b32 s6, s4
	s_mov_b32 s7, s4
	s_mov_b32 s5, s4
	v_cndmask_b32_e32 v38, v18, v2, vcc
	v_cmp_lt_i32_e32 vcc, v37, v101
	s_or_b64 vcc, s[0:1], vcc
	v_sub_f32_e32 v2, v2, v38
	v_cndmask_b32_e32 v37, v237, v2, vcc
	v_exp_f32_e32 v2, v19
	v_cndmask_b32_e64 v18, 0, -v38, vcc
	v_cmp_lt_f32_e32 vcc, s22, v19
	v_add_f32_e32 v2, 1.0, v2
	v_log_f32_e32 v2, v2
	s_nop 0
	v_cndmask_b32_e32 v38, v2, v19, vcc
	v_or_b32_e32 v2, 1, v41
	v_cmp_lt_i32_e32 vcc, v2, v101
	s_or_b64 vcc, s[0:1], vcc
	v_sub_f32_e32 v19, v19, v38
	v_cndmask_b32_e64 v2, 0, -v38, vcc
	v_cndmask_b32_e32 v38, v237, v19, vcc
	v_exp_f32_e32 v19, v3
	v_cmp_lt_f32_e32 vcc, s22, v3
	v_cvt_pk_bf16_f32 v2, v34, v2
	v_add_f32_e32 v19, 1.0, v19
	v_log_f32_e32 v19, v19
	s_nop 0
	v_cndmask_b32_e32 v39, v19, v3, vcc
	v_or_b32_e32 v19, 33, v41
	v_cmp_lt_i32_e32 vcc, v19, v101
	s_or_b64 vcc, s[0:1], vcc
	v_sub_f32_e32 v3, v3, v39
	v_cndmask_b32_e64 v19, 0, -v39, vcc
	v_cndmask_b32_e32 v39, v237, v3, vcc
	v_exp_f32_e32 v3, v20
	v_cmp_lt_f32_e32 vcc, s22, v20
	v_cvt_pk_bf16_f32 v18, v18, v19
	v_add_f32_e32 v3, 1.0, v3
	v_log_f32_e32 v3, v3
	s_nop 0
	v_cndmask_b32_e32 v40, v3, v20, vcc
	v_or_b32_e32 v3, 2, v41
	v_cmp_lt_i32_e32 vcc, v3, v101
	s_or_b64 vcc, s[0:1], vcc
	v_sub_f32_e32 v20, v20, v40
	v_cndmask_b32_e64 v3, 0, -v40, vcc
	v_cndmask_b32_e32 v40, v237, v20, vcc
	v_exp_f32_e32 v20, v4
	v_cmp_lt_f32_e32 vcc, s22, v4
	v_add_f32_e32 v20, 1.0, v20
	v_log_f32_e32 v20, v20
	s_nop 0
	v_cndmask_b32_e32 v42, v20, v4, vcc
	v_or_b32_e32 v20, 34, v41
	v_cmp_lt_i32_e32 vcc, v20, v101
	s_or_b64 vcc, s[0:1], vcc
	v_sub_f32_e32 v4, v4, v42
	v_cndmask_b32_e64 v20, 0, -v42, vcc
	v_cndmask_b32_e32 v42, v237, v4, vcc
	v_exp_f32_e32 v4, v21
	v_cmp_lt_f32_e32 vcc, s22, v21
	v_add_f32_e32 v4, 1.0, v4
	v_log_f32_e32 v4, v4
	s_nop 0
	v_cndmask_b32_e32 v43, v4, v21, vcc
	v_or_b32_e32 v4, 3, v41
	v_cmp_lt_i32_e32 vcc, v4, v101
	s_or_b64 vcc, s[0:1], vcc
	v_sub_f32_e32 v21, v21, v43
	v_cndmask_b32_e64 v4, 0, -v43, vcc
	v_cndmask_b32_e32 v43, v237, v21, vcc
; DI int crow(int r, int hi) { return (r & 3) + 8 * (r >> 2) + 4 * hi; }
; DI float ex2(float x) { return __builtin_amdgcn_exp2f(x); }
; DI float lg2(float x) { return __builtin_amdgcn_logf(x); }
; template <int S> DI bf16x8 pack8(const f32x16& x) { u32x4 p; p[0] = cvtpk(x[8 * S], x[8 * S + 1]); p[1] = cvtpk(x[8 * S + 2], x[8 * S + 3]); p[2] = cvtpk(x[8 * S + 4], x[8 * S + 5]); p[3] = cvtpk(x[8 * S + 6], x[8 * S + 7]); return __builtin_bit_cast(bf16x8, p); }
; DI void sb_unit(LAS char* lds, int b, int h, int qb, const bf16_t* __restrict__ Q, const bf16_t* __restrict__ K, const bf16_t* __restrict__ VT, const bf16_t* __restrict__ G, bf16_t* __restrict__ MIX) {
;     ...
;             for (int r = 0; r < 16; ++r) {
;                 { const float z = p0[r]; const float lg = (z > 30.f) ? z : lg2(1.0f + ex2(z)); const bool valid = !diag || (kv0 + crow(r, hi) < tq); L0[r] = valid ? -lg : 0.f; p0[r] = valid ? (z - lg) : -1e30f; }
;                 { const float z = p1[r]; const float lg = (z > 30.f) ? z : lg2(1.0f + ex2(z)); const bool valid = !diag || (kv0 + 32 + crow(r, hi) < tq); L1[r] = valid ? -lg : 0.f; p1[r] = valid ? (z - lg) : -1e30f; }
;             }
;             const bf16x8 Lh0 = pack8<0>(L0), Lh1 = pack8<1>(L0), Lh2 = pack8<0>(L1), Lh3 = pack8<1>(L1);
	v_exp_f32_e32 v21, v5
	v_cmp_lt_f32_e32 vcc, s22, v5
	v_cvt_pk_bf16_f32 v3, v3, v4
	v_add_f32_e32 v21, 1.0, v21
	v_log_f32_e32 v21, v21
	s_nop 0
	v_cndmask_b32_e32 v44, v21, v5, vcc
	v_or_b32_e32 v21, 35, v41
	v_cmp_lt_i32_e32 vcc, v21, v101
	s_or_b64 vcc, s[0:1], vcc
	v_sub_f32_e32 v5, v5, v44
	v_cndmask_b32_e64 v21, 0, -v44, vcc
	v_cndmask_b32_e32 v44, v237, v5, vcc
	v_exp_f32_e32 v5, v22
	v_cmp_lt_f32_e32 vcc, s22, v22
	v_cvt_pk_bf16_f32 v19, v20, v21
	v_add_f32_e32 v5, 1.0, v5
	v_log_f32_e32 v5, v5
	s_nop 0
	v_cndmask_b32_e32 v45, v5, v22, vcc
	v_or_b32_e32 v5, 8, v41
	v_cmp_lt_i32_e32 vcc, v5, v101
	s_or_b64 vcc, s[0:1], vcc
	v_sub_f32_e32 v22, v22, v45
	v_cndmask_b32_e64 v5, 0, -v45, vcc
	v_cndmask_b32_e32 v45, v237, v22, vcc
	v_exp_f32_e32 v22, v6
	v_cmp_lt_f32_e32 vcc, s22, v6
	v_add_f32_e32 v22, 1.0, v22
	v_log_f32_e32 v22, v22
	s_nop 0
	v_cndmask_b32_e32 v46, v22, v6, vcc
	v_or_b32_e32 v22, 40, v41
	v_cmp_lt_i32_e32 vcc, v22, v101
	s_or_b64 vcc, s[0:1], vcc
	v_sub_f32_e32 v6, v6, v46
	v_cndmask_b32_e64 v22, 0, -v46, vcc
	v_cndmask_b32_e32 v46, v237, v6, vcc
	v_exp_f32_e32 v6, v23
	v_cmp_lt_f32_e32 vcc, s22, v23
	v_add_f32_e32 v6, 1.0, v6
	v_log_f32_e32 v6, v6
	s_nop 0
	v_cndmask_b32_e32 v47, v6, v23, vcc
	v_or_b32_e32 v6, 9, v41
	v_cmp_lt_i32_e32 vcc, v6, v101
	s_or_b64 vcc, s[0:1], vcc
	v_sub_f32_e32 v23, v23, v47
	v_cndmask_b32_e64 v6, 0, -v47, vcc
	v_cndmask_b32_e32 v47, v237, v23, vcc
	v_exp_f32_e32 v23, v7
	v_cmp_lt_f32_e32 vcc, s22, v7
	v_cvt_pk_bf16_f32 v4, v5, v6
	v_add_f32_e32 v23, 1.0, v23
	v_log_f32_e32 v23, v23
	s_nop 0
	v_cndmask_b32_e32 v48, v23, v7, vcc
	v_or_b32_e32 v23, 41, v41
	v_cmp_lt_i32_e32 vcc, v23, v101
	s_or_b64 vcc, s[0:1], vcc
	v_sub_f32_e32 v7, v7, v48
	v_cndmask_b32_e64 v23, 0, -v48, vcc
	v_cndmask_b32_e32 v48, v237, v7, vcc
	v_exp_f32_e32 v7, v24
	v_cmp_lt_f32_e32 vcc, s22, v24
	v_cvt_pk_bf16_f32 v20, v22, v23
	v_add_f32_e32 v7, 1.0, v7
	v_log_f32_e32 v7, v7
	s_nop 0
	v_cndmask_b32_e32 v49, v7, v24, vcc
	v_or_b32_e32 v7, 10, v41
	v_cmp_lt_i32_e32 vcc, v7, v101
	s_or_b64 vcc, s[0:1], vcc
	v_sub_f32_e32 v24, v24, v49
	v_cndmask_b32_e64 v7, 0, -v49, vcc
	v_cndmask_b32_e32 v49, v237, v24, vcc
	v_exp_f32_e32 v24, v8
	v_cmp_lt_f32_e32 vcc, s22, v8
	v_add_f32_e32 v24, 1.0, v24
	v_log_f32_e32 v24, v24
	s_nop 0
	v_cndmask_b32_e32 v50, v24, v8, vcc
	v_or_b32_e32 v24, 42, v41
	v_cmp_lt_i32_e32 vcc, v24, v101
	s_or_b64 vcc, s[0:1], vcc
	v_sub_f32_e32 v8, v8, v50
	v_cndmask_b32_e64 v24, 0, -v50, vcc
	v_cndmask_b32_e32 v50, v237, v8, vcc
	v_exp_f32_e32 v8, v25
	v_cmp_lt_f32_e32 vcc, s22, v25
	v_add_f32_e32 v8, 1.0, v8
	v_log_f32_e32 v8, v8
	s_nop 0
	v_cndmask_b32_e32 v51, v8, v25, vcc
	v_or_b32_e32 v8, 11, v41
	v_cmp_lt_i32_e32 vcc, v8, v101
	s_or_b64 vcc, s[0:1], vcc
	v_sub_f32_e32 v25, v25, v51
	v_cndmask_b32_e64 v8, 0, -v51, vcc
	v_cndmask_b32_e32 v51, v237, v25, vcc
	v_exp_f32_e32 v25, v9
	v_cmp_lt_f32_e32 vcc, s22, v9
	v_cvt_pk_bf16_f32 v5, v7, v8
	v_add_f32_e32 v25, 1.0, v25
	v_log_f32_e32 v25, v25
	s_nop 0
	v_cndmask_b32_e32 v52, v25, v9, vcc
	v_or_b32_e32 v25, 43, v41
	v_cmp_lt_i32_e32 vcc, v25, v101
	s_or_b64 vcc, s[0:1], vcc
	v_sub_f32_e32 v9, v9, v52
	v_cndmask_b32_e64 v25, 0, -v52, vcc
	v_cndmask_b32_e32 v52, v237, v9, vcc
	v_exp_f32_e32 v9, v26
	v_cmp_lt_f32_e32 vcc, s22, v26
	v_cvt_pk_bf16_f32 v21, v24, v25
	v_mov_b64_e32 v[24:25], s[6:7]
	v_add_f32_e32 v9, 1.0, v9
	v_log_f32_e32 v9, v9
	v_mov_b64_e32 v[22:23], s[4:5]
	v_cndmask_b32_e32 v53, v9, v26, vcc
	v_or_b32_e32 v9, 16, v41
	v_cmp_lt_i32_e32 vcc, v9, v101
	s_or_b64 vcc, s[0:1], vcc
	v_sub_f32_e32 v26, v26, v53
	v_cndmask_b32_e64 v9, 0, -v53, vcc
	v_cndmask_b32_e32 v53, v237, v26, vcc
	v_exp_f32_e32 v26, v10
	v_cmp_lt_f32_e32 vcc, s22, v10
	v_add_f32_e32 v26, 1.0, v26
	v_log_f32_e32 v26, v26
	s_nop 0
	v_cndmask_b32_e32 v54, v26, v10, vcc
	v_or_b32_e32 v26, 48, v41
	v_cmp_lt_i32_e32 vcc, v26, v101
	s_or_b64 vcc, s[0:1], vcc
	v_sub_f32_e32 v10, v10, v54
	v_cndmask_b32_e64 v26, 0, -v54, vcc
	v_cndmask_b32_e32 v54, v237, v10, vcc
	v_exp_f32_e32 v10, v27
	v_cmp_lt_f32_e32 vcc, s22, v27
	v_add_f32_e32 v10, 1.0, v10
	v_log_f32_e32 v10, v10
	s_nop 0
	v_cndmask_b32_e32 v55, v10, v27, vcc
	v_or_b32_e32 v10, 17, v41
	v_cmp_lt_i32_e32 vcc, v10, v101
	s_or_b64 vcc, s[0:1], vcc
	v_sub_f32_e32 v27, v27, v55
	v_cndmask_b32_e64 v10, 0, -v55, vcc
	v_cndmask_b32_e32 v55, v237, v27, vcc
	v_exp_f32_e32 v27, v11
	v_cmp_lt_f32_e32 vcc, s22, v11
	v_add_f32_e32 v27, 1.0, v27
	v_log_f32_e32 v27, v27
	s_nop 0
	v_cndmask_b32_e32 v56, v27, v11, vcc
	v_or_b32_e32 v27, 49, v41
	v_cmp_lt_i32_e32 vcc, v27, v101
	s_or_b64 vcc, s[0:1], vcc
	v_sub_f32_e32 v11, v11, v56
	v_cndmask_b32_e64 v27, 0, -v56, vcc
	v_cndmask_b32_e32 v56, v237, v11, vcc
	v_exp_f32_e32 v11, v28
	v_cmp_lt_f32_e32 vcc, s22, v28
	v_cvt_pk_bf16_f32 v108, v26, v27
	v_add_f32_e32 v11, 1.0, v11
	v_log_f32_e32 v11, v11
	s_nop 0
	v_cndmask_b32_e32 v57, v11, v28, vcc
	v_or_b32_e32 v11, 18, v41
	v_cmp_lt_i32_e32 vcc, v11, v101
	s_or_b64 vcc, s[0:1], vcc
	v_sub_f32_e32 v28, v28, v57
	v_cndmask_b32_e64 v11, 0, -v57, vcc
	v_cndmask_b32_e32 v57, v237, v28, vcc
	v_exp_f32_e32 v28, v12
	v_cmp_lt_f32_e32 vcc, s22, v12
	v_add_f32_e32 v28, 1.0, v28
	v_log_f32_e32 v28, v28
	s_nop 0
	v_cndmask_b32_e32 v58, v28, v12, vcc
	v_or_b32_e32 v28, 50, v41
	v_cmp_lt_i32_e32 vcc, v28, v101
	s_or_b64 vcc, s[0:1], vcc
	v_sub_f32_e32 v12, v12, v58
	v_cndmask_b32_e64 v28, 0, -v58, vcc
	v_cndmask_b32_e32 v58, v237, v12, vcc
	v_exp_f32_e32 v12, v29
	v_cmp_lt_f32_e32 vcc, s22, v29
	v_add_f32_e32 v12, 1.0, v12
	v_log_f32_e32 v12, v12
	s_nop 0
	v_cndmask_b32_e32 v59, v12, v29, vcc
	v_or_b32_e32 v12, 19, v41
	v_cmp_lt_i32_e32 vcc, v12, v101
; #define MFMA32(a, b, c) __builtin_amdgcn_mfma_f32_32x32x16_bf16((a), (b), (c), 0, 0, 0)
; DI int crow(int r, int hi) { return (r & 3) + 8 * (r >> 2) + 4 * hi; }
; DI float ex2(float x) { return __builtin_amdgcn_exp2f(x); }
; DI float lg2(float x) { return __builtin_amdgcn_logf(x); }
; template <int S> DI bf16x8 pack8(const f32x16& x) { u32x4 p; p[0] = cvtpk(x[8 * S], x[8 * S + 1]); p[1] = cvtpk(x[8 * S + 2], x[8 * S + 3]); p[2] = cvtpk(x[8 * S + 4], x[8 * S + 5]); p[3] = cvtpk(x[8 * S + 6], x[8 * S + 7]); return __builtin_bit_cast(bf16x8, p); }
; #define SB_PV(ks, pa) { const bf16x8 v0 = ldsv(Vt + off128(r32, 2 * (ks) + hi)), v1 = ldsv(Vt + off128(32 + r32, 2 * (ks) + hi)); o0 = MFMA32(v0, pa, o0); o1 = MFMA32(v1, pa, o1); }
; DI void sb_unit(LAS char* lds, int b, int h, int qb, const bf16_t* __restrict__ Q, const bf16_t* __restrict__ K, const bf16_t* __restrict__ VT, const bf16_t* __restrict__ G, bf16_t* __restrict__ MIX) {
;     ...
;             for (int r = 0; r < 16; ++r) {
;                 { const float z = p0[r]; const float lg = (z > 30.f) ? z : lg2(1.0f + ex2(z)); const bool valid = !diag || (kv0 + crow(r, hi) < tq); L0[r] = valid ? -lg : 0.f; p0[r] = valid ? (z - lg) : -1e30f; }
;                 { const float z = p1[r]; const float lg = (z > 30.f) ? z : lg2(1.0f + ex2(z)); const bool valid = !diag || (kv0 + 32 + crow(r, hi) < tq); L1[r] = valid ? -lg : 0.f; p1[r] = valid ? (z - lg) : -1e30f; }
;             }
;             const bf16x8 Lh0 = pack8<0>(L0), Lh1 = pack8<1>(L0), Lh2 = pack8<0>(L1), Lh3 = pack8<1>(L1);
;             f32x16 C0 = splat16(carry), C1 = C0;
;             C0 = MFMA32(tp0, Lh0, C0); C0 = MFMA32(tp1, Lh1, C0); C0 = MFMA32(ones, Lh2, C0); C0 = MFMA32(ones, Lh3, C0);
;             C1 = MFMA32(tp0, Lh2, C1); C1 = MFMA32(tp1, Lh3, C1);
;             const float cn = C0[0] + L0[0];
;             carry = __shfl(cn, r32, 64);
; #pragma unroll
;             for (int r = 0; r < 16; ++r) { p0[r] = ex2(p0[r] + C0[r]); p1[r] = ex2(p1[r] + C1[r]); }
;             const bf16x8 pa0 = pack8<0>(p0), pa1 = pack8<1>(p0), pa2 = pack8<0>(p1), pa3 = pack8<1>(p1);
;     ...
;             SB_PV(0, pa0) SB_PV(1, pa1) SB_PV(2, pa2) SB_PV(3, pa3)
;     ...
;             done = __all(carry < -152.f) ? 1 : 0;
	s_or_b64 vcc, s[0:1], vcc
	v_sub_f32_e32 v29, v29, v59
	v_cndmask_b32_e64 v12, 0, -v59, vcc
	v_cndmask_b32_e32 v59, v237, v29, vcc
	v_exp_f32_e32 v29, v13
	v_cmp_lt_f32_e32 vcc, s22, v13
	v_add_f32_e32 v29, 1.0, v29
	v_log_f32_e32 v29, v29
	s_nop 0
	v_cndmask_b32_e32 v60, v29, v13, vcc
	v_or_b32_e32 v29, 51, v41
	v_cmp_lt_i32_e32 vcc, v29, v101
	s_or_b64 vcc, s[0:1], vcc
	v_sub_f32_e32 v13, v13, v60
	v_cndmask_b32_e64 v29, 0, -v60, vcc
	v_cndmask_b32_e32 v60, v237, v13, vcc
	v_exp_f32_e32 v13, v30
	v_cmp_lt_f32_e32 vcc, s22, v30
	v_cvt_pk_bf16_f32 v109, v28, v29
	v_add_f32_e32 v13, 1.0, v13
	v_log_f32_e32 v13, v13
	s_nop 0
	v_cndmask_b32_e32 v13, v13, v30, vcc
	v_cmp_lt_i32_e32 vcc, v61, v101
	s_or_b64 vcc, s[0:1], vcc
	s_nop 0
	v_cndmask_b32_e64 v66, 0, -v13, vcc
	v_sub_f32_e32 v13, v30, v13
	v_cndmask_b32_e32 v61, v237, v13, vcc
	v_exp_f32_e32 v13, v14
	v_cmp_lt_f32_e32 vcc, s22, v14
	v_or_b32_e32 v30, 56, v41
	v_add_f32_e32 v13, 1.0, v13
	v_log_f32_e32 v13, v13
	s_nop 0
	v_cndmask_b32_e32 v13, v13, v14, vcc
	v_cmp_lt_i32_e32 vcc, v30, v101
	s_or_b64 vcc, s[0:1], vcc
	v_or_b32_e32 v30, 57, v41
	v_cndmask_b32_e64 v67, 0, -v13, vcc
	v_sub_f32_e32 v13, v14, v13
	v_cndmask_b32_e32 v62, v237, v13, vcc
	v_exp_f32_e32 v13, v31
	v_cmp_lt_f32_e32 vcc, s22, v31
	v_or_b32_e32 v14, 25, v41
	v_add_f32_e32 v13, 1.0, v13
	v_log_f32_e32 v13, v13
	s_nop 0
	v_cndmask_b32_e32 v13, v13, v31, vcc
	v_cmp_lt_i32_e32 vcc, v14, v101
	s_or_b64 vcc, s[0:1], vcc
	s_nop 0
	v_cndmask_b32_e64 v14, 0, -v13, vcc
	v_sub_f32_e32 v13, v31, v13
	v_cndmask_b32_e32 v63, v237, v13, vcc
	v_exp_f32_e32 v13, v15
	v_cmp_lt_f32_e32 vcc, s22, v15
	v_cvt_pk_bf16_f32 v31, v11, v12
	v_add_f32_e32 v13, 1.0, v13
	v_log_f32_e32 v13, v13
	s_nop 0
	v_cndmask_b32_e32 v13, v13, v15, vcc
	v_cmp_lt_i32_e32 vcc, v30, v101
	s_or_b64 vcc, s[0:1], vcc
	v_or_b32_e32 v30, 58, v41
	v_cndmask_b32_e64 v110, 0, -v13, vcc
	v_sub_f32_e32 v13, v15, v13
	v_cndmask_b32_e32 v64, v237, v13, vcc
	v_exp_f32_e32 v13, v32
	v_cmp_lt_f32_e32 vcc, s22, v32
	v_or_b32_e32 v15, 26, v41
	v_cvt_pk_bf16_f32 v110, v67, v110
	v_add_f32_e32 v13, 1.0, v13
	v_log_f32_e32 v13, v13
	s_nop 0
	v_cndmask_b32_e32 v13, v13, v32, vcc
	v_cmp_lt_i32_e32 vcc, v15, v101
	s_or_b64 vcc, s[0:1], vcc
	s_nop 0
	v_cndmask_b32_e64 v15, 0, -v13, vcc
	v_sub_f32_e32 v13, v32, v13
	v_cndmask_b32_e32 v65, v237, v13, vcc
	v_exp_f32_e32 v13, v16
	v_cmp_lt_f32_e32 vcc, s22, v16
	v_cvt_pk_bf16_f32 v32, v66, v14
	v_add_f32_e32 v13, 1.0, v13
	v_log_f32_e32 v13, v13
	s_nop 0
	v_cndmask_b32_e32 v13, v13, v16, vcc
	v_cmp_lt_i32_e32 vcc, v30, v101
	s_or_b64 vcc, s[0:1], vcc
	v_or_b32_e32 v30, 59, v41
	v_cndmask_b32_e64 v111, 0, -v13, vcc
	v_sub_f32_e32 v13, v16, v13
	v_cndmask_b32_e32 v112, v237, v13, vcc
	v_exp_f32_e32 v13, v33
	v_cmp_lt_f32_e32 vcc, s22, v33
	v_or_b32_e32 v16, 27, v41
	v_add_f32_e32 v13, 1.0, v13
	v_log_f32_e32 v13, v13
	s_nop 0
	v_cndmask_b32_e32 v13, v13, v33, vcc
	v_cmp_lt_i32_e32 vcc, v16, v101
	s_or_b64 vcc, s[0:1], vcc
	s_nop 0
	v_cndmask_b32_e64 v16, 0, -v13, vcc
	v_sub_f32_e32 v13, v33, v13
	v_cndmask_b32_e32 v113, v237, v13, vcc
	v_exp_f32_e32 v13, v17
	v_cmp_lt_f32_e32 vcc, s22, v17
	v_cvt_pk_bf16_f32 v33, v15, v16
	v_add_f32_e32 v13, 1.0, v13
	v_log_f32_e32 v13, v13
	s_nop 0
	v_cndmask_b32_e32 v13, v13, v17, vcc
	v_cmp_lt_i32_e32 vcc, v30, v101
	s_or_b64 vcc, s[0:1], vcc
	v_cvt_pk_bf16_f32 v30, v9, v10
	v_cndmask_b32_e64 v41, 0, -v13, vcc
	v_sub_f32_e32 v13, v17, v13
	v_cndmask_b32_e32 v114, v237, v13, vcc
	v_mfma_f32_32x32x16_bf16 v[2:17], v[84:87], v[2:5], 0
	v_cvt_pk_bf16_f32 v111, v111, v41
	v_and_or_b32 v41, v238, 64, v100
	v_lshlrev_b32_e32 v41, 2, v41
	s_mov_b32 s0, s4
	v_writelane_b32 v254, s0, 48
	v_mfma_f32_32x32x16_bf16 v[2:17], v[88:91], v[30:33], v[2:17]
	s_nop 0
	v_writelane_b32 v254, s1, 49
	v_writelane_b32 v254, s2, 50
	v_writelane_b32 v254, s3, 51
	s_mov_b32 s0, 0xc3180000
	v_mfma_f32_32x32x16_bf16 v[2:17], v[22:25], v[18:21], v[2:17]
	v_mfma_f32_32x32x16_bf16 v[2:17], v[22:25], v[108:111], v[2:17]
	v_mfma_f32_32x32x16_bf16 v[18:33], v[84:87], v[18:21], 0
	s_nop 10
	v_add_f32_e32 v10, v10, v53
	v_add_f32_e32 v11, v11, v55
	v_add_f32_e32 v34, v34, v2
	v_add_f32_e32 v2, v2, v36
	v_add_f32_e32 v3, v3, v38
	v_add_f32_e32 v4, v4, v40
	v_add_f32_e32 v5, v5, v43
	v_mfma_f32_32x32x16_bf16 v[18:33], v[88:91], v[108:111], v[18:33]
	v_add_f32_e32 v6, v6, v45
	v_add_f32_e32 v7, v7, v47
	v_add_f32_e32 v8, v8, v49
	v_add_f32_e32 v9, v9, v51
	v_exp_f32_e32 v10, v10
	v_exp_f32_e32 v11, v11
	v_add_f32_e32 v12, v12, v57
	v_add_f32_e32 v13, v13, v59
	v_exp_f32_e32 v2, v2
	v_exp_f32_e32 v3, v3
	v_exp_f32_e32 v4, v4
	v_exp_f32_e32 v5, v5
	v_exp_f32_e32 v6, v6
	v_exp_f32_e32 v7, v7
	v_exp_f32_e32 v8, v8
	v_exp_f32_e32 v9, v9
	v_exp_f32_e32 v12, v12
	v_exp_f32_e32 v13, v13
	v_add_f32_e32 v21, v44, v21
	v_cvt_pk_bf16_f32 v44, v10, v11
	v_add3_u32 v10, 0, v104, v103
	v_add_f32_e32 v18, v37, v18
	v_add_f32_e32 v19, v39, v19
	v_add_f32_e32 v20, v42, v20
	v_add_f32_e32 v22, v46, v22
	v_add_f32_e32 v23, v48, v23
	v_add_f32_e32 v24, v50, v24
	v_add_f32_e32 v25, v52, v25
	v_add_f32_e32 v26, v54, v26
	v_add_f32_e32 v27, v56, v27
	v_add_f32_e32 v28, v58, v28
	v_add_f32_e32 v29, v60, v29
	v_add_f32_e32 v14, v14, v61
	v_add_f32_e32 v30, v62, v30
	v_add_f32_e32 v15, v15, v63
	v_add_f32_e32 v31, v64, v31
	v_add_f32_e32 v16, v16, v65
	v_add_f32_e32 v32, v112, v32
	v_add_f32_e32 v17, v17, v113
	v_add_f32_e32 v33, v114, v33
	v_cvt_pk_bf16_f32 v2, v2, v3
	v_cvt_pk_bf16_f32 v3, v4, v5
	v_cvt_pk_bf16_f32 v4, v6, v7
	v_cvt_pk_bf16_f32 v5, v8, v9
	v_cvt_pk_bf16_f32 v45, v12, v13
	ds_read_b128 v[6:9], v10 offset:8192
	ds_read_b128 v[10:13], v10 offset:12288
	v_exp_f32_e32 v18, v18
	v_exp_f32_e32 v19, v19
	v_exp_f32_e32 v20, v20
	v_exp_f32_e32 v21, v21
	v_exp_f32_e32 v22, v22
	v_exp_f32_e32 v23, v23
	v_exp_f32_e32 v24, v24
	v_exp_f32_e32 v25, v25
	v_exp_f32_e32 v26, v26
	v_exp_f32_e32 v27, v27
	v_exp_f32_e32 v28, v28
	v_exp_f32_e32 v29, v29
	v_exp_f32_e32 v14, v14
	v_exp_f32_e32 v30, v30
	v_exp_f32_e32 v15, v15
	v_exp_f32_e32 v31, v31
	v_exp_f32_e32 v16, v16
	v_exp_f32_e32 v32, v32
	v_exp_f32_e32 v17, v17
	v_exp_f32_e32 v33, v33
	ds_bpermute_b32 v34, v41, v34
	v_cvt_pk_bf16_f32 v46, v14, v15
	v_cvt_pk_bf16_f32 v47, v16, v17
	v_cvt_pk_bf16_f32 v40, v18, v19
	v_cvt_pk_bf16_f32 v41, v20, v21
	v_cvt_pk_bf16_f32 v42, v22, v23
	v_cvt_pk_bf16_f32 v43, v24, v25
	v_cvt_pk_bf16_f32 v36, v26, v27
	v_cvt_pk_bf16_f32 v37, v28, v29
	v_cvt_pk_bf16_f32 v38, v30, v31
	v_cvt_pk_bf16_f32 v39, v32, v33
	s_waitcnt lgkmcnt(2)
; DI float ex2(float x) { return __builtin_amdgcn_exp2f(x); }
; template <int S> DI bf16x8 pack8(const f32x16& x) { u32x4 p; p[0] = cvtpk(x[8 * S], x[8 * S + 1]); p[1] = cvtpk(x[8 * S + 2], x[8 * S + 3]); p[2] = cvtpk(x[8 * S + 4], x[8 * S + 5]); p[3] = cvtpk(x[8 * S + 6], x[8 * S + 7]); return __builtin_bit_cast(bf16x8, p); }
; #define SB_PV(ks, pa) { const bf16x8 v0 = ldsv(Vt + off128(r32, 2 * (ks) + hi)), v1 = ldsv(Vt + off128(32 + r32, 2 * (ks) + hi)); o0 = MFMA32(v0, pa, o0); o1 = MFMA32(v1, pa, o1); }
; DI void sb_unit(LAS char* lds, int b, int h, int qb, const bf16_t* __restrict__ Q, const bf16_t* __restrict__ K, const bf16_t* __restrict__ VT, const bf16_t* __restrict__ G, bf16_t* __restrict__ MIX) {
;     ...
;             for (int r = 0; r < 16; ++r) { p0[r] = ex2(p0[r] + C0[r]); p1[r] = ex2(p1[r] + C1[r]); }
;             const bf16x8 pa0 = pack8<0>(p0), pa1 = pack8<1>(p0), pa2 = pack8<0>(p1), pa3 = pack8<1>(p1);
;     ...
;             SB_PV(0, pa0) SB_PV(1, pa1) SB_PV(2, pa2) SB_PV(3, pa3)
;     ...
;             done = __all(carry < -152.f) ? 1 : 0;
; __global__ void __launch_bounds__(512) fwd_megakernel(Args a) {
;     ...
;             const int q = slot >> 16, idx = slot & 0xffff;
;             int ub, uh, uq; bool isdf = true;
;             if (q < 4) { ub = q >> 1; uh = 3 - (q & 1); uq = 63 - idx; }
;             else { const int y = q - 4;
;                 if (idx < 64) { ub = y >> 1; uh = 1 - (y & 1); uq = 63 - idx; }
;                 else { const int v = idx - 64; const int bh = 4 * y + (v & 3); ub = bh >> 3; uh = bh & 7; uq = 31 - (v >> 2); isdf = false; } }
	v_mfma_f32_32x32x16_bf16 v[18:33], v[6:9], v[2:5], 0
	v_add3_u32 v52, 0, v105, v103
	ds_read_b128 v[48:51], v52 offset:8192
	ds_read_b128 v[52:55], v52 offset:12288
	s_waitcnt lgkmcnt(2)
	v_cmp_gt_f32_e32 vcc, s0, v34
	s_cmp_eq_u64 vcc, exec
	s_cselect_b64 s[0:1], -1, 0
	v_mfma_f32_32x32x16_bf16 v[2:17], v[10:13], v[2:5], 0
	s_waitcnt lgkmcnt(1)
	v_mfma_f32_32x32x16_bf16 v[18:33], v[48:51], v[44:47], v[18:33]
	v_add3_u32 v48, 0, v106, v103
	s_waitcnt lgkmcnt(0)
	v_mfma_f32_32x32x16_bf16 v[2:17], v[52:55], v[44:47], v[2:17]
	ds_read_b128 v[44:47], v48 offset:8192
	ds_read_b128 v[48:51], v48 offset:12288
	s_waitcnt lgkmcnt(1)
	v_mfma_f32_32x32x16_bf16 v[18:33], v[44:47], v[40:43], v[18:33]
	v_add3_u32 v44, 0, v107, v103
	s_waitcnt lgkmcnt(0)
	v_mfma_f32_32x32x16_bf16 v[2:17], v[48:51], v[40:43], v[2:17]
	ds_read_b128 v[40:43], v44 offset:8192
	ds_read_b128 v[44:47], v44 offset:12288
	s_waitcnt lgkmcnt(1)
	v_mfma_f32_32x32x16_bf16 v[18:33], v[40:43], v[36:39], v[18:33]
	s_waitcnt lgkmcnt(0)
	v_mfma_f32_32x32x16_bf16 v[2:17], v[44:47], v[36:39], v[2:17]
	v_cndmask_b32_e64 v36, 0, 1, s[0:1]
	s_branch .LBB0_414
.LBB0_367:
	s_and_b64 vcc, exec, s[6:7]
	s_cbranch_vccz .LBB0_363
	s_bfe_u32 s0, s4, 0x10010
	s_lshr_b32 s14, s4, 17
	s_xor_b32 s16, s0, 3
	s_cmp_lt_u32 s5, 32
	s_cbranch_scc1 .Lhv_ok
	s_add_i32 s5, s5, 3
.Lhv_ok:
	s_sub_i32 s15, 63, s5
	s_mov_b64 s[0:1], -1

; #define LAS __attribute__((address_space(3)))
; #define MFMA32(a, b, c) __builtin_amdgcn_mfma_f32_32x32x16_bf16((a), (b), (c), 0, 0, 0)
; DI float ex2(float x) { return __builtin_amdgcn_exp2f(x); }
; #define PIN4(x) asm volatile("" : "+v"(x[0]), "+v"(x[1]), "+v"(x[2]), "+v"(x[3]))
; #define MEMFENCE() asm volatile("" ::: "memory")
; DI void df_scores(const LAS char* Kst, const DfCtx& c, f32x16& p, f32x16& q, int kv0) {
;     const float bb = c.c0 + c.sl * (float)kv0;
;     bf16x8 k0[4], k1[4];
; #pragma unroll
;     for (int d0 = 0; d0 < 4; ++d0) k0[d0] = ldsv(Kst + c.kad[d0]);
;     MEMFENCE();
; #pragma unroll
;     for (int r = 0; r < 16; ++r) p[r] = __builtin_fmaf(c.sl, (float)((r & 3) + 8 * (r >> 2)), bb);
;     PIN4(k0);
; #pragma unroll
;     for (int d0 = 0; d0 < 4; ++d0) p = MFMA32(k0[d0], c.qf[d0], p);
; #pragma unroll
;     for (int d0 = 0; d0 < 4; ++d0) k1[d0] = ldsv(Kst + c.kad[d0] + 8192);
;     MEMFENCE();
;     { const float ba = bb + c.sl * 32.0f;
; #pragma unroll
;       for (int r = 0; r < 16; ++r) q[r] = __builtin_fmaf(c.sl, (float)((r & 3) + 8 * (r >> 2)), ba); }
;     PIN4(k1);
; #pragma unroll
;     for (int d0 = 0; d0 < 4; ++d0) q = MFMA32(k1[d0], c.qf[d0], q);
; }
; template <bool PV> DI void df_pv_exp(const LAS char* Vst, const DfCtx& c, const bf16x8 (&pw)[4], f32x16 (&O)[4], f32x16& p, f32x16& q, bf16x8 (&pwN)[4], float& l, bool dg, int kv0) {
;     bf16x8 v0[4];
;     if (PV) {
; #pragma unroll
;         for (int ks = 0; ks < 4; ++ks) v0[ks] = ldsv(Vst + c.vad[ks]);
;         MEMFENCE(); }
; #pragma unroll
;     for (int r = 0; r < 16; ++r) p[r] = ex2(p[r]);
.LBB0_377:
	v_readlane_b32 s0, v255, 21
	s_lshl_b32 s0, s0, 3
	v_bitop3_b32 v2, v43, v42, 15 bitop3:0x78
	v_lshlrev_b32_e32 v0, 8, v41
	v_xor_b32_e32 v2, s0, v2
	s_or_b32 s1, s0, 2
	v_lshl_add_u32 v240, v2, 4, v0
	v_bitop3_b32 v2, v42, s1, 15 bitop3:0x6c
	v_xor_b32_e32 v2, v2, v43
	s_or_b32 s1, s0, 4
	v_lshl_add_u32 v241, v2, 4, v0
	v_bitop3_b32 v2, v42, s1, 15 bitop3:0x6c
	s_or_b32 s0, s0, 6
	v_xor_b32_e32 v2, v2, v43
	v_lshlrev_b32_e32 v52, 2, v43
	v_bitop3_b32 v3, v42, s0, 15 bitop3:0x6c
	v_lshl_add_u32 v242, v2, 4, v0
	v_sub_u32_e32 v2, v44, v52
	v_xor_b32_e32 v3, v3, v43
	v_cvt_f32_i32_e32 v2, v2
	v_lshl_add_u32 v243, v3, 4, v0
	s_lshl_b32 s12, s98, 6
	v_cvt_f32_u32_e32 v0, s12
	v_add_u32_e32 v234, 0, v243
	v_add_u32_e32 v251, 0, v240
	v_add_u32_e32 v252, 0, v241
	v_add_u32_e32 v232, 0, v242
	ds_read_b128 v[18:21], v234
	ds_read_b128 v[22:25], v232
	ds_read_b128 v[26:29], v251
	ds_read_b128 v[30:33], v252
	v_readlane_b32 s0, v254, 63
	s_waitcnt lgkmcnt(0)
	s_nop 0
	v_fma_f32 v244, -v179, v2, -s0
	v_fma_f32 v0, v179, v0, v244
	v_fma_f32 v2, 0, v179, v0
	v_add_f32_e32 v3, v179, v0
	v_pk_fma_f32 v[4:5], v[178:179], s[8:9], v[0:1] op_sel:[1,0,0] op_sel_hi:[1,1,0]
	v_pk_fma_f32 v[6:7], v[178:179], s[28:29], v[0:1] op_sel:[1,0,0] op_sel_hi:[1,1,0]
	v_pk_fma_f32 v[8:9], v[178:179], s[30:31], v[0:1] op_sel:[1,0,0] op_sel_hi:[1,1,0]
	v_pk_fma_f32 v[10:11], v[178:179], s[34:35], v[0:1] op_sel:[1,0,0] op_sel_hi:[1,1,0]
	v_pk_fma_f32 v[12:13], v[178:179], s[10:11], v[0:1] op_sel:[1,0,0] op_sel_hi:[1,1,0]
	v_pk_fma_f32 v[14:15], v[178:179], s[20:21], v[0:1] op_sel:[1,0,0] op_sel_hi:[1,1,0]
	v_pk_fma_f32 v[16:17], v[178:179], s[2:3], v[0:1] op_sel:[1,0,0] op_sel_hi:[1,1,0]
	ds_read_b128 v[34:37], v234 offset:8192
	ds_read_b128 v[46:49], v232 offset:8192
	ds_read_b128 v[54:57], v252 offset:8192
	ds_read_b128 v[58:61], v251 offset:8192
	s_nop 0
	v_mfma_f32_32x32x16_bf16 v[2:17], v[26:29], v[130:133], v[2:17]
	v_fmac_f32_e32 v0, 0x42000000, v179
	v_fma_f32 v26, v179, s34, v0
	v_fma_f32 v27, v179, s35, v0
	v_fma_f32 v28, v179, s10, v0
	v_fma_f32 v29, v179, s11, v0
	s_waitcnt lgkmcnt(0)
	s_add_i32 s15, s23, -2
	s_cmp_lt_i32 s98, s15
	s_nop 0
	v_mfma_f32_32x32x16_bf16 v[2:17], v[30:33], v[134:137], v[2:17]
	v_fma_f32 v30, v179, s20, v0
	v_fma_f32 v31, v179, s21, v0
	v_fma_f32 v32, v179, s2, v0
	v_fma_f32 v33, v179, s3, v0
	s_nop 0
	v_mfma_f32_32x32x16_bf16 v[2:17], v[22:25], v[138:141], v[2:17]
	v_fma_f32 v22, v179, s28, v0
	v_fma_f32 v23, v179, s29, v0
	v_fma_f32 v24, v179, s30, v0
	v_fma_f32 v25, v179, s31, v0
	s_nop 0
	v_mfma_f32_32x32x16_bf16 v[2:17], v[18:21], v[142:145], v[2:17]
	v_fma_f32 v18, 0, v179, v0
	v_add_f32_e32 v19, v179, v0
	v_fma_f32 v20, v179, s8, v0
	v_fma_f32 v21, v179, s9, v0
	s_nop 1
	v_mfma_f32_32x32x16_bf16 v[18:33], v[58:61], v[130:133], v[18:33]
	s_nop 4
	v_exp_f32_e32 v45, v2
	v_exp_f32_e32 v51, v5
	v_exp_f32_e32 v2, v10
	v_exp_f32_e32 v10, v14
	v_exp_f32_e32 v16, v16
	v_exp_f32_e32 v17, v17
	v_mfma_f32_32x32x16_bf16 v[18:33], v[54:57], v[134:137], v[18:33]
	v_mfma_f32_32x32x16_bf16 v[18:33], v[46:49], v[138:141], v[18:33]
	v_exp_f32_e32 v48, v3
	v_exp_f32_e32 v49, v4
	v_exp_f32_e32 v3, v11
	v_exp_f32_e32 v11, v15
	v_mfma_f32_32x32x16_bf16 v[18:33], v[34:37], v[142:145], v[18:33]
	v_exp_f32_e32 v34, v6
	v_exp_f32_e32 v35, v7
	v_exp_f32_e32 v36, v8
	v_exp_f32_e32 v37, v9
	v_exp_f32_e32 v6, v12
	v_exp_f32_e32 v7, v13
	s_nop 5
	v_exp_f32_e32 v0, v18
	v_exp_f32_e32 v46, v19
	v_exp_f32_e32 v47, v20
	v_exp_f32_e32 v50, v21
	v_exp_f32_e32 v14, v22
	v_exp_f32_e32 v15, v23
	v_exp_f32_e32 v20, v24
	v_exp_f32_e32 v21, v25
	v_exp_f32_e32 v4, v26
	v_exp_f32_e32 v5, v27
	v_exp_f32_e32 v8, v28
	v_exp_f32_e32 v9, v29
	v_exp_f32_e32 v12, v30
	v_exp_f32_e32 v13, v31
	v_exp_f32_e32 v18, v32
	v_exp_f32_e32 v19, v33
	s_cbranch_scc1 .LBB0_379
; template <bool PV> DI void df_pv_exp(const LAS char* Vst, const DfCtx& c, const bf16x8 (&pw)[4], f32x16 (&O)[4], f32x16& p, f32x16& q, bf16x8 (&pwN)[4], float& l, bool dg, int kv0) {
;     ...
;     if (dg) { const int lim = c.tq - kv0 - 4 * c.hi;
; #pragma unroll
;         for (int r = 0; r < 16; ++r) { if ((r & 3) + 8 * (r >> 2) > lim) p[r] = 0.f; if (32 + (r & 3) + 8 * (r >> 2) > lim) q[r] = 0.f; } }
	v_or_b32_e32 v22, s12, v52
	v_sub_u32_e32 v22, v44, v22
	v_cmp_gt_i32_e64 s[92:93], 26, v22
	v_cmp_gt_i32_e64 s[96:97], 27, v22
	v_cmp_gt_i32_e64 s[88:89], 25, v22
	s_and_b64 s[16:17], s[96:97], s[92:93]
	v_cmp_gt_i32_e64 s[86:87], 24, v22
	v_cndmask_b32_e64 v16, v16, 0, s[16:17]
	s_and_b64 s[16:17], s[16:17], s[88:89]
	v_cmp_gt_i32_e64 s[84:85], 19, v22
	v_cndmask_b32_e64 v11, v11, 0, s[16:17]
	s_and_b64 s[16:17], s[16:17], s[86:87]
	v_cmp_gt_i32_e64 s[82:83], 18, v22
	v_cndmask_b32_e64 v10, v10, 0, s[16:17]
	s_and_b64 s[16:17], s[16:17], s[84:85]
	v_cmp_gt_i32_e64 s[80:81], 17, v22
	v_cndmask_b32_e64 v7, v7, 0, s[16:17]
	s_and_b64 s[16:17], s[16:17], s[82:83]
	v_cmp_gt_i32_e64 s[78:79], 16, v22
	v_cndmask_b32_e64 v6, v6, 0, s[16:17]
	s_and_b64 s[16:17], s[16:17], s[80:81]
	v_cmp_gt_i32_e64 s[76:77], 11, v22
	v_cndmask_b32_e64 v3, v3, 0, s[16:17]
	s_and_b64 s[16:17], s[16:17], s[78:79]
	v_cmp_gt_i32_e64 s[74:75], 10, v22
	v_cndmask_b32_e64 v2, v2, 0, s[16:17]
	s_and_b64 s[16:17], s[16:17], s[76:77]
	v_cmp_gt_i32_e64 s[72:73], 9, v22
	v_cndmask_b32_e64 v37, v37, 0, s[16:17]
	s_and_b64 s[16:17], s[16:17], s[74:75]
	v_cmp_gt_i32_e64 s[70:71], 8, v22
	v_cndmask_b32_e64 v36, v36, 0, s[16:17]
	s_and_b64 s[16:17], s[16:17], s[72:73]
	v_cmp_gt_i32_e64 s[68:69], 3, v22
	v_cndmask_b32_e64 v35, v35, 0, s[16:17]
	s_and_b64 s[16:17], s[16:17], s[70:71]
	v_cmp_gt_i32_e64 s[66:67], 2, v22
	v_cndmask_b32_e64 v34, v34, 0, s[16:17]
	s_and_b64 s[16:17], s[16:17], s[68:69]
	v_cmp_gt_i32_e64 s[64:65], 1, v22
	v_cndmask_b32_e64 v51, v51, 0, s[16:17]
	s_and_b64 s[16:17], s[16:17], s[66:67]
	v_cmp_gt_i32_e64 s[62:63], 0, v22
	v_cndmask_b32_e64 v49, v49, 0, s[16:17]
	s_and_b64 s[16:17], s[16:17], s[64:65]
	v_cmp_gt_i32_e64 s[94:95], 58, v22
	v_cndmask_b32_e64 v48, v48, 0, s[16:17]
	s_and_b64 s[16:17], s[16:17], s[62:63]
	v_cmp_gt_i32_e64 s[62:63], 59, v22
	v_cmp_gt_i32_e64 s[90:91], 57, v22
	v_cndmask_b32_e64 v45, v45, 0, s[16:17]
	s_and_b64 s[16:17], s[62:63], s[94:95]
	v_cmp_gt_i32_e64 s[58:59], 56, v22
	v_cndmask_b32_e64 v18, v18, 0, s[16:17]
	s_and_b64 s[16:17], s[16:17], s[90:91]
	v_cmp_gt_i32_e64 s[56:57], 51, v22
	v_cndmask_b32_e64 v13, v13, 0, s[16:17]
	s_and_b64 s[16:17], s[16:17], s[58:59]
	v_cmp_gt_i32_e64 s[54:55], 50, v22
	v_cndmask_b32_e64 v12, v12, 0, s[16:17]
	s_and_b64 s[16:17], s[16:17], s[56:57]
	v_cmp_gt_i32_e64 s[52:53], 49, v22
	v_cndmask_b32_e64 v9, v9, 0, s[16:17]
	s_and_b64 s[16:17], s[16:17], s[54:55]
	v_cmp_gt_i32_e64 s[50:51], 48, v22
	v_cndmask_b32_e64 v8, v8, 0, s[16:17]
	s_and_b64 s[16:17], s[16:17], s[52:53]
	v_cmp_gt_i32_e64 s[48:49], 43, v22
	v_cndmask_b32_e64 v5, v5, 0, s[16:17]
	s_and_b64 s[16:17], s[16:17], s[50:51]
	v_cmp_gt_i32_e64 s[46:47], 42, v22
	v_cndmask_b32_e64 v4, v4, 0, s[16:17]
	s_and_b64 s[16:17], s[16:17], s[48:49]
	v_cmp_gt_i32_e64 s[42:43], 41, v22
	v_cndmask_b32_e64 v21, v21, 0, s[16:17]
	s_and_b64 s[16:17], s[16:17], s[46:47]
	v_cmp_gt_i32_e64 s[40:41], 40, v22
	v_cndmask_b32_e64 v20, v20, 0, s[16:17]
	s_and_b64 s[16:17], s[16:17], s[42:43]
	v_cmp_gt_i32_e64 s[38:39], 35, v22
	v_cndmask_b32_e64 v15, v15, 0, s[16:17]
	s_and_b64 s[16:17], s[16:17], s[40:41]
	v_cmp_gt_i32_e64 s[36:37], 34, v22
	v_cndmask_b32_e64 v14, v14, 0, s[16:17]
	s_and_b64 s[16:17], s[16:17], s[38:39]
	v_cmp_gt_i32_e64 s[0:1], 33, v22
	v_cndmask_b32_e64 v50, v50, 0, s[16:17]
	s_and_b64 s[16:17], s[16:17], s[36:37]
	v_cmp_gt_i32_e32 vcc, 32, v22
	s_and_b64 s[0:1], s[16:17], s[0:1]
	v_readlane_b32 s64, v255, 0
	v_cndmask_b32_e64 v46, v46, 0, s[0:1]
	s_and_b64 s[0:1], s[0:1], vcc
	v_cndmask_b32_e64 v17, v17, 0, s[96:97]
	v_readlane_b32 s72, v255, 8
	v_readlane_b32 s73, v255, 9
	v_readlane_b32 s76, v255, 12
	v_readlane_b32 s77, v255, 13
	v_readlane_b32 s78, v255, 14
	v_readlane_b32 s79, v255, 15
	v_cndmask_b32_e64 v19, v19, 0, s[62:63]
	v_cndmask_b32_e64 v47, v47, 0, s[16:17]
	v_cndmask_b32_e64 v0, v0, 0, s[0:1]
	v_readlane_b32 s65, v255, 1
	v_readlane_b32 s66, v255, 2
	v_readlane_b32 s67, v255, 3
	v_readlane_b32 s68, v255, 4
	v_readlane_b32 s69, v255, 5
	v_readlane_b32 s70, v255, 6
	v_readlane_b32 s71, v255, 7
	v_readlane_b32 s74, v255, 10
	v_readlane_b32 s75, v255, 11

; #define WAIT_BAR0() asm volatile("s_waitcnt vmcnt(0) lgkmcnt(0)\n\ts_barrier" ::: "memory")
; DI void df_unit(LAS char* lds, int b, int h, int qb, const bf16_t* __restrict__ Q, const bf16_t* __restrict__ K, const bf16_t* __restrict__ VT, const bf16_t* __restrict__ G, bf16_t* __restrict__ MIX,
;                 float lam, float Mb  , const float* __restrict__ subg) {
;     ...
;     WAIT_BAR0();
;     if (mp == 0) {
;         const float i1 = 1.0f / l; float ss = 0.f;
; #pragma unroll
;         for (int db = 0; db < 4; ++db)
;             {
; #pragma unroll
;               for (int r = 0; r < 16; ++r) { const float v = O[db][r] * i1 - Xch[(wq * 64 + db * 16 + r) * 64 + lane2]; O[db][r] = v; ss += v * v; } asm volatile("" : "+v"(O[db]), "+v"(ss) :: "memory"); }
;         ss += __shfl_xor(ss, 32);
.LBB0_411:
	s_waitcnt vmcnt(0) lgkmcnt(0)
	s_barrier
	s_cmpk_gt_u32 s5, 0xff
	s_cbranch_scc1 .LBB0_345
	v_div_scale_f32 v69, s[0:1], v0, v0, 1.0
	v_rcp_f32_e32 v70, v69
	v_div_scale_f32 v71, vcc, 1.0, v0, 1.0
	s_lshl_b32 s0, s5, 8
	v_fma_f32 v72, -v69, v70, 1.0
	v_fmac_f32_e32 v70, v72, v70
	v_mul_f32_e32 v72, v71, v70
	v_fma_f32 v73, -v69, v72, v71
	v_fmac_f32_e32 v72, v73, v70
	v_lshl_add_u32 v86, v67, 2, 0
	s_and_b32 s1, s0, 0xc000
	v_fma_f32 v69, -v69, v72, v71
	v_add_u32_e32 v87, s1, v86
	v_div_fmas_f32 v69, v69, v70, v72
	ds_read2st64_b32 v[70:71], v87 offset1:1
	ds_read2st64_b32 v[72:73], v87 offset0:2 offset1:3
	ds_read2st64_b32 v[74:75], v87 offset0:4 offset1:5
	ds_read2st64_b32 v[76:77], v87 offset0:6 offset1:7
	v_div_fixup_f32 v0, v69, v0, 1.0
	s_or_b32 s0, s0, 0x3f00
	s_waitcnt lgkmcnt(2)
	v_pk_fma_f32 v[52:53], v[52:53], v[0:1], v[72:73] op_sel_hi:[1,0,1] neg_lo:[0,0,1] neg_hi:[0,0,1]
	v_pk_fma_f32 v[50:51], v[50:51], v[0:1], v[70:71] op_sel_hi:[1,0,1] neg_lo:[0,0,1] neg_hi:[0,0,1]
	v_pk_mul_f32 v[72:73], v[52:53], v[52:53]
	v_pk_mul_f32 v[70:71], v[50:51], v[50:51]
	s_waitcnt lgkmcnt(0)
	v_pk_fma_f32 v[56:57], v[56:57], v[0:1], v[76:77] op_sel_hi:[1,0,1] neg_lo:[0,0,1] neg_hi:[0,0,1]
	ds_read2st64_b32 v[76:77], v87 offset0:8 offset1:9
	v_add_f32_e32 v69, v70, v71
	v_pk_fma_f32 v[54:55], v[54:55], v[0:1], v[74:75] op_sel_hi:[1,0,1] neg_lo:[0,0,1] neg_hi:[0,0,1]
	v_add_f32_e32 v69, v69, v72
	v_pk_mul_f32 v[74:75], v[54:55], v[54:55]
	v_add_f32_e32 v69, v69, v73
	v_add_f32_e32 v69, v69, v74
	v_pk_mul_f32 v[78:79], v[56:57], v[56:57]
	ds_read2st64_b32 v[80:81], v87 offset0:10 offset1:11
	ds_read2st64_b32 v[82:83], v87 offset0:12 offset1:13
	ds_read2st64_b32 v[84:85], v87 offset0:14 offset1:15
	v_add_f32_e32 v69, v69, v75
	s_waitcnt lgkmcnt(3)
	v_pk_fma_f32 v[58:59], v[58:59], v[0:1], v[76:77] op_sel_hi:[1,0,1] neg_lo:[0,0,1] neg_hi:[0,0,1]
	v_add_f32_e32 v69, v69, v78
	v_pk_mul_f32 v[76:77], v[58:59], v[58:59]
	v_add_f32_e32 v69, v69, v79
	s_waitcnt lgkmcnt(2)
	v_pk_fma_f32 v[60:61], v[60:61], v[0:1], v[80:81] op_sel_hi:[1,0,1] neg_lo:[0,0,1] neg_hi:[0,0,1]
	v_add_f32_e32 v69, v69, v76
	v_pk_mul_f32 v[80:81], v[60:61], v[60:61]
	v_add_f32_e32 v69, v69, v77
	s_waitcnt lgkmcnt(1)
	v_pk_fma_f32 v[62:63], v[62:63], v[0:1], v[82:83] op_sel_hi:[1,0,1] neg_lo:[0,0,1] neg_hi:[0,0,1]
	v_add_f32_e32 v69, v69, v80
	v_pk_mul_f32 v[82:83], v[62:63], v[62:63]
	v_add_f32_e32 v69, v69, v81
	s_waitcnt lgkmcnt(0)
	v_pk_fma_f32 v[64:65], v[64:65], v[0:1], v[84:85] op_sel_hi:[1,0,1] neg_lo:[0,0,1] neg_hi:[0,0,1]
	v_add_f32_e32 v69, v69, v82
	v_pk_mul_f32 v[84:85], v[64:65], v[64:65]
	v_add_f32_e32 v69, v69, v83
	v_add_f32_e32 v69, v69, v84
	v_add_f32_e32 v69, v69, v85
	ds_read2st64_b32 v[70:71], v87 offset0:16 offset1:17
	ds_read2st64_b32 v[72:73], v87 offset0:18 offset1:19
	ds_read2st64_b32 v[74:75], v87 offset0:20 offset1:21
	ds_read2st64_b32 v[76:77], v87 offset0:22 offset1:23
	v_readlane_b32 s1, v255, 23
	s_waitcnt lgkmcnt(3)
	v_pk_fma_f32 v[34:35], v[34:35], v[0:1], v[70:71] op_sel_hi:[1,0,1] neg_lo:[0,0,1] neg_hi:[0,0,1]
	s_waitcnt lgkmcnt(2)
	v_pk_fma_f32 v[36:37], v[36:37], v[0:1], v[72:73] op_sel_hi:[1,0,1] neg_lo:[0,0,1] neg_hi:[0,0,1]
	v_pk_mul_f32 v[70:71], v[34:35], v[34:35]
	s_waitcnt lgkmcnt(1)
	v_pk_fma_f32 v[38:39], v[38:39], v[0:1], v[74:75] op_sel_hi:[1,0,1] neg_lo:[0,0,1] neg_hi:[0,0,1]
	v_add_f32_e32 v69, v69, v70
	v_add_f32_e32 v69, v69, v71
	v_pk_mul_f32 v[70:71], v[36:37], v[36:37]
	ds_read2st64_b32 v[72:73], v87 offset0:24 offset1:25
	v_add_f32_e32 v69, v69, v70
	v_add_f32_e32 v69, v69, v71
	v_pk_mul_f32 v[70:71], v[38:39], v[38:39]
	s_waitcnt lgkmcnt(1)
	v_pk_fma_f32 v[40:41], v[40:41], v[0:1], v[76:77] op_sel_hi:[1,0,1] neg_lo:[0,0,1] neg_hi:[0,0,1]
	v_add_f32_e32 v69, v69, v70
	v_add_f32_e32 v69, v69, v71
	v_pk_mul_f32 v[70:71], v[40:41], v[40:41]
	s_waitcnt lgkmcnt(0)
	v_pk_fma_f32 v[42:43], v[42:43], v[0:1], v[72:73] op_sel_hi:[1,0,1] neg_lo:[0,0,1] neg_hi:[0,0,1]
	v_add_f32_e32 v69, v69, v70
	v_add_f32_e32 v69, v69, v71
	ds_read2st64_b32 v[70:71], v87 offset0:26 offset1:27
	ds_read2st64_b32 v[74:75], v87 offset0:28 offset1:29
	ds_read2st64_b32 v[76:77], v87 offset0:30 offset1:31
	v_pk_mul_f32 v[72:73], v[42:43], v[42:43]
	s_lshl_b32 s98, s6, 1
	v_add_f32_e32 v69, v69, v72
	s_waitcnt lgkmcnt(2)
	v_pk_fma_f32 v[44:45], v[44:45], v[0:1], v[70:71] op_sel_hi:[1,0,1] neg_lo:[0,0,1] neg_hi:[0,0,1]
	v_add_f32_e32 v69, v69, v73
	v_pk_mul_f32 v[70:71], v[44:45], v[44:45]
	s_waitcnt lgkmcnt(1)
	v_pk_fma_f32 v[46:47], v[46:47], v[0:1], v[74:75] op_sel_hi:[1,0,1] neg_lo:[0,0,1] neg_hi:[0,0,1]
	v_add_f32_e32 v69, v69, v70
	v_add_f32_e32 v69, v69, v71
	v_pk_mul_f32 v[70:71], v[46:47], v[46:47]
	s_waitcnt lgkmcnt(0)
	v_pk_fma_f32 v[48:49], v[48:49], v[0:1], v[76:77] op_sel_hi:[1,0,1] neg_lo:[0,0,1] neg_hi:[0,0,1]
	v_add_f32_e32 v69, v69, v70
	v_add_f32_e32 v69, v69, v71
	v_pk_mul_f32 v[70:71], v[48:49], v[48:49]
	s_mov_b32 s4, 0x3f4ccccd
	v_add_f32_e32 v69, v69, v70
	v_add_f32_e32 v69, v69, v71
	ds_read2st64_b32 v[70:71], v87 offset0:32 offset1:33
	ds_read2st64_b32 v[72:73], v87 offset0:34 offset1:35
	ds_read2st64_b32 v[74:75], v87 offset0:36 offset1:37
	ds_read2st64_b32 v[76:77], v87 offset0:38 offset1:39
	s_waitcnt lgkmcnt(3)
	v_pk_fma_f32 v[18:19], v[18:19], v[0:1], v[70:71] op_sel_hi:[1,0,1] neg_lo:[0,0,1] neg_hi:[0,0,1]
	s_nop 0
	v_pk_mul_f32 v[70:71], v[18:19], v[18:19]
	s_waitcnt lgkmcnt(2)
	v_pk_fma_f32 v[20:21], v[20:21], v[0:1], v[72:73] op_sel_hi:[1,0,1] neg_lo:[0,0,1] neg_hi:[0,0,1]
	v_add_f32_e32 v69, v69, v70
	v_add_f32_e32 v69, v69, v71
	v_pk_mul_f32 v[70:71], v[20:21], v[20:21]
	s_waitcnt lgkmcnt(1)
; DI void swz_in(u32x4 t, u32x2& g0, u32x2& g1) { auto r0 = __builtin_amdgcn_permlane32_swap(t.x, t.z, false, false); auto r1 = __builtin_amdgcn_permlane32_swap(t.y, t.w, false, false); g0.x = r0[0]; g0.y = r1[0]; g1.x = r0[1]; g1.y = r1[1]; }
; DI void df_unit(LAS char* lds, int b, int h, int qb, const bf16_t* __restrict__ Q, const bf16_t* __restrict__ K, const bf16_t* __restrict__ VT, const bf16_t* __restrict__ G, bf16_t* __restrict__ MIX,
;                 float lam, float Mb  , const float* __restrict__ subg) {
;     ...
;         const float i1 = 1.0f / l; float ss = 0.f;
; #pragma unroll
;         for (int db = 0; db < 4; ++db)
;             {
; #pragma unroll
;               for (int r = 0; r < 16; ++r) { const float v = O[db][r] * i1 - Xch[(wq * 64 + db * 16 + r) * 64 + lane2]; O[db][r] = v; ss += v * v; } asm volatile("" : "+v"(O[db]), "+v"(ss) :: "memory"); }
;         ss += __shfl_xor(ss, 32);
;         const float rs = 0.8f / sqrtf(ss * (1.0f / 128.0f) + EPS);
;         const size_t trow = (size_t)(b * SEQ + tq2);
; #pragma unroll
;         for (int db = 0; db < 4; ++db)
; #pragma unroll
;             for (int gp = 0; gp < 2; ++gp) { const int dc = 32 * db + 16 * gp + 8 * hi2, d0 = 32 * db + 16 * gp + 4 * hi2, d1 = d0 + 8; const int r0 = 8 * gp, r1 = 8 * gp + 4;
;                 u32x2 g0, g1; swz_in(*(const u32x4*)(G + trow * 512 + h * 128 + dc), g0, g1);
;                 const f32x4 s0 = *(const f32x4*)(subg + d0), s1 = *(const f32x4*)(subg + d1);
	v_pk_fma_f32 v[22:23], v[22:23], v[0:1], v[74:75] op_sel_hi:[1,0,1] neg_lo:[0,0,1] neg_hi:[0,0,1]
	v_add_f32_e32 v69, v69, v70
	v_add_f32_e32 v69, v69, v71
	v_pk_mul_f32 v[70:71], v[22:23], v[22:23]
	ds_read2st64_b32 v[72:73], v87 offset0:40 offset1:41
	v_add_f32_e32 v69, v69, v70
	s_waitcnt lgkmcnt(1)
	v_pk_fma_f32 v[24:25], v[24:25], v[0:1], v[76:77] op_sel_hi:[1,0,1] neg_lo:[0,0,1] neg_hi:[0,0,1]
	v_add_f32_e32 v69, v69, v71
	v_pk_mul_f32 v[70:71], v[24:25], v[24:25]
	s_waitcnt lgkmcnt(0)
	v_pk_fma_f32 v[26:27], v[26:27], v[0:1], v[72:73] op_sel_hi:[1,0,1] neg_lo:[0,0,1] neg_hi:[0,0,1]
	v_add_f32_e32 v69, v69, v70
	v_add_f32_e32 v69, v69, v71
	ds_read2st64_b32 v[70:71], v87 offset0:42 offset1:43
	ds_read2st64_b32 v[74:75], v87 offset0:44 offset1:45
	ds_read2st64_b32 v[76:77], v87 offset0:46 offset1:47
	v_pk_mul_f32 v[72:73], v[26:27], v[26:27]
	s_waitcnt lgkmcnt(2)
	v_pk_fma_f32 v[28:29], v[28:29], v[0:1], v[70:71] op_sel_hi:[1,0,1] neg_lo:[0,0,1] neg_hi:[0,0,1]
	v_add_f32_e32 v69, v69, v72
	v_add_f32_e32 v69, v69, v73
	v_pk_mul_f32 v[70:71], v[28:29], v[28:29]
	s_waitcnt lgkmcnt(1)
	v_pk_fma_f32 v[30:31], v[30:31], v[0:1], v[74:75] op_sel_hi:[1,0,1] neg_lo:[0,0,1] neg_hi:[0,0,1]
	v_add_f32_e32 v69, v69, v70
	v_add_f32_e32 v69, v69, v71
	v_pk_mul_f32 v[70:71], v[30:31], v[30:31]
	s_waitcnt lgkmcnt(0)
	v_pk_fma_f32 v[32:33], v[32:33], v[0:1], v[76:77] op_sel_hi:[1,0,1] neg_lo:[0,0,1] neg_hi:[0,0,1]
	v_add_f32_e32 v69, v69, v70
	v_add_f32_e32 v69, v69, v71
	v_pk_mul_f32 v[70:71], v[32:33], v[32:33]
	s_nop 0
	v_add_f32_e32 v69, v69, v70
	v_add_f32_e32 v69, v69, v71
	ds_read2st64_b32 v[70:71], v87 offset0:48 offset1:49
	ds_read2st64_b32 v[72:73], v87 offset0:50 offset1:51
	ds_read2st64_b32 v[74:75], v87 offset0:52 offset1:53
	ds_read2st64_b32 v[76:77], v87 offset0:54 offset1:55
	s_waitcnt lgkmcnt(3)
	v_pk_fma_f32 v[2:3], v[2:3], v[0:1], v[70:71] op_sel_hi:[1,0,1] neg_lo:[0,0,1] neg_hi:[0,0,1]
	s_nop 0
	v_pk_mul_f32 v[70:71], v[2:3], v[2:3]
	s_waitcnt lgkmcnt(2)
	v_pk_fma_f32 v[4:5], v[4:5], v[0:1], v[72:73] op_sel_hi:[1,0,1] neg_lo:[0,0,1] neg_hi:[0,0,1]
	v_add_f32_e32 v69, v69, v70
	v_add_f32_e32 v69, v69, v71
	v_pk_mul_f32 v[70:71], v[4:5], v[4:5]
	s_waitcnt lgkmcnt(1)
	v_pk_fma_f32 v[6:7], v[6:7], v[0:1], v[74:75] op_sel_hi:[1,0,1] neg_lo:[0,0,1] neg_hi:[0,0,1]
	v_add_f32_e32 v69, v69, v70
	v_add_f32_e32 v69, v69, v71
	v_pk_mul_f32 v[70:71], v[6:7], v[6:7]
	ds_read2st64_b32 v[72:73], v87 offset0:56 offset1:57
	v_add_f32_e32 v69, v69, v70
	s_waitcnt lgkmcnt(1)
	v_pk_fma_f32 v[8:9], v[8:9], v[0:1], v[76:77] op_sel_hi:[1,0,1] neg_lo:[0,0,1] neg_hi:[0,0,1]
	v_add_f32_e32 v69, v69, v71
	v_pk_mul_f32 v[70:71], v[8:9], v[8:9]
	s_waitcnt lgkmcnt(0)
	v_pk_fma_f32 v[10:11], v[10:11], v[0:1], v[72:73] op_sel_hi:[1,0,1] neg_lo:[0,0,1] neg_hi:[0,0,1]
	v_add_f32_e32 v69, v69, v70
	v_add_f32_e32 v69, v69, v71
	ds_read2st64_b32 v[70:71], v87 offset0:58 offset1:59
	ds_read2st64_b32 v[74:75], v87 offset0:60 offset1:61
	ds_read_b32 v76, v87 offset:15872
	v_pk_mul_f32 v[72:73], v[10:11], v[10:11]
	s_waitcnt lgkmcnt(2)
	v_pk_fma_f32 v[12:13], v[12:13], v[0:1], v[70:71] op_sel_hi:[1,0,1] neg_lo:[0,0,1] neg_hi:[0,0,1]
	v_add_f32_e32 v69, v69, v72
	v_add_f32_e32 v69, v69, v73
	v_pk_mul_f32 v[70:71], v[12:13], v[12:13]
	s_waitcnt lgkmcnt(1)
	v_pk_fma_f32 v[14:15], v[14:15], v[0:1], v[74:75] op_sel_hi:[1,0,1] neg_lo:[0,0,1] neg_hi:[0,0,1]
	v_add_f32_e32 v69, v69, v70
	v_add_u32_e32 v70, s0, v86
	ds_read_b32 v77, v70
	v_readlane_b32 s0, v255, 20
	v_add_f32_e32 v69, v69, v71
	v_pk_mul_f32 v[70:71], v[14:15], v[14:15]
	s_add_i32 s0, s0, s1
	v_add_f32_e32 v69, v69, v70
	s_waitcnt lgkmcnt(0)
	v_pk_fma_f32 v[16:17], v[16:17], v[0:1], v[76:77] op_sel_hi:[1,0,1] neg_lo:[0,0,1] neg_hi:[0,0,1]
	v_and_or_b32 v82, v68, 31, s0
	v_add_f32_e32 v69, v69, v71
	v_pk_mul_f32 v[70:71], v[16:17], v[16:17]
	v_ashrrev_i32_e32 v83, 31, v82
	v_readlane_b32 s0, v253, 12
	v_add_f32_e32 v0, v69, v70
	v_lshlrev_b64 v[68:69], 10, v[82:83]
	v_readlane_b32 s1, v253, 13
	v_add_f32_e32 v84, v0, v71
	v_lshrrev_b32_e32 v0, 1, v67
	v_lshl_add_u64 v[68:69], s[0:1], 0, v[68:69]
	v_lshl_add_u64 v[68:69], v[68:69], 0, s[98:99]
	v_and_b32_e32 v0, 16, v0
	v_lshl_add_u64 v[68:69], v[68:69], 0, v[0:1]
	global_load_dwordx4 v[70:73], v[68:69], off
	global_load_dwordx4 v[74:77], v0, s[72:73]
	global_load_dwordx4 v[78:81], v0, s[72:73] offset:32
	global_load_dwordx4 v[112:115], v[68:69], off offset:32
	global_load_dwordx4 v[116:119], v0, s[72:73] offset:64
	global_load_dwordx4 v[120:123], v0, s[72:73] offset:96
	global_load_dwordx4 v[124:127], v[68:69], off offset:64
	global_load_dwordx4 v[128:131], v0, s[72:73] offset:128
	global_load_dwordx4 v[132:135], v0, s[72:73] offset:160
	global_load_dwordx4 v[136:139], v[68:69], off offset:96
	global_load_dwordx4 v[140:143], v0, s[72:73] offset:192
	global_load_dwordx4 v[144:147], v0, s[72:73] offset:224
	global_load_dwordx4 v[148:151], v[68:69], off offset:128
	global_load_dwordx4 v[152:155], v0, s[72:73] offset:256
	global_load_dwordx4 v[156:159], v0, s[72:73] offset:288
	global_load_dwordx4 v[160:163], v[68:69], off offset:160
	global_load_dwordx4 v[164:167], v0, s[72:73] offset:320
	global_load_dwordx4 v[168:171], v0, s[72:73] offset:352
	global_load_dwordx4 v[172:175], v[68:69], off offset:192
	global_load_dwordx4 v[176:179], v0, s[72:73] offset:384
	global_load_dwordx4 v[180:183], v0, s[72:73] offset:416
	global_load_dwordx4 v[184:187], v[68:69], off offset:224
	global_load_dwordx4 v[188:191], v0, s[72:73] offset:448
	global_load_dwordx4 v[192:195], v0, s[72:73] offset:480
	ds_bpermute_b32 v66, v66, v84
	v_mov_b32_e32 v67, 0x358637bd
	s_mov_b32 s0, 0xf800000
	v_lshlrev_b64 v[82:83], 11, v[82:83]
	s_waitcnt lgkmcnt(0)
; DI unsigned cvtpk(float lo, float hi) { f32x2 v = {lo, hi}; bf16x2 b = __builtin_convertvector(v, bf16x2); return __builtin_bit_cast(unsigned, b); }
; DI float bf_lo(unsigned w) { return __uint_as_float(w << 16); }
; DI float bf_hi(unsigned w) { return __uint_as_float(w & 0xffff0000u); }
; DI void swz_in(u32x4 t, u32x2& g0, u32x2& g1) { auto r0 = __builtin_amdgcn_permlane32_swap(t.x, t.z, false, false); auto r1 = __builtin_amdgcn_permlane32_swap(t.y, t.w, false, false); g0.x = r0[0]; g0.y = r1[0]; g1.x = r0[1]; g1.y = r1[1]; }
; DI u32x4 swz_out(u32x2 w0, u32x2 w1) { auto r0 = __builtin_amdgcn_permlane32_swap(w0.x, w1.x, false, false); auto r1 = __builtin_amdgcn_permlane32_swap(w0.y, w1.y, false, false); u32x4 o; o.x = r0[0]; o.y = r1[0]; o.z = r0[1]; o.w = r1[1]; return o; }
; DI void df_unit(LAS char* lds, int b, int h, int qb, const bf16_t* __restrict__ Q, const bf16_t* __restrict__ K, const bf16_t* __restrict__ VT, const bf16_t* __restrict__ G, bf16_t* __restrict__ MIX,
;                 float lam, float Mb  , const float* __restrict__ subg) {
;     ...
;         const float rs = 0.8f / sqrtf(ss * (1.0f / 128.0f) + EPS);
;         const size_t trow = (size_t)(b * SEQ + tq2);
; #pragma unroll
;         for (int db = 0; db < 4; ++db)
; #pragma unroll
;             for (int gp = 0; gp < 2; ++gp) { const int dc = 32 * db + 16 * gp + 8 * hi2, d0 = 32 * db + 16 * gp + 4 * hi2, d1 = d0 + 8; const int r0 = 8 * gp, r1 = 8 * gp + 4;
;                 u32x2 g0, g1; swz_in(*(const u32x4*)(G + trow * 512 + h * 128 + dc), g0, g1);
;                 const f32x4 s0 = *(const f32x4*)(subg + d0), s1 = *(const f32x4*)(subg + d1);
;                 u32x2 w0, w1;
;                 w0.x = cvtpk(O[db][r0] * rs * s0[0] * bf_lo(g0.x), O[db][r0 + 1] * rs * s0[1] * bf_hi(g0.x)); w0.y = cvtpk(O[db][r0 + 2] * rs * s0[2] * bf_lo(g0.y), O[db][r0 + 3] * rs * s0[3] * bf_hi(g0.y));
;                 w1.x = cvtpk(O[db][r1] * rs * s1[0] * bf_lo(g1.x), O[db][r1 + 1] * rs * s1[1] * bf_hi(g1.x)); w1.y = cvtpk(O[db][r1 + 2] * rs * s1[2] * bf_lo(g1.y), O[db][r1 + 3] * rs * s1[3] * bf_hi(g1.y));
;                 *(u32x4*)(MIX + trow * 1024 + 512 + h * 128 + dc) = swz_out(w0, w1); asm volatile("" ::: "memory"); }
	v_add_f32_e32 v66, v84, v66
	v_fmamk_f32 v66, v66, 0x3c000000, v67
	v_mul_f32_e32 v67, 0x4f800000, v66
	v_cmp_gt_f32_e32 vcc, s0, v66
	s_nop 1
	v_cndmask_b32_e32 v66, v66, v67, vcc
	v_sqrt_f32_e32 v67, v66
	s_nop 0
	v_add_u32_e32 v84, -1, v67
	v_fma_f32 v85, -v84, v67, v66
	v_cmp_ge_f32_e64 s[0:1], 0, v85
	v_add_u32_e32 v85, 1, v67
	s_nop 0
	v_cndmask_b32_e64 v84, v67, v84, s[0:1]
	v_fma_f32 v67, -v85, v67, v66
	v_cmp_lt_f32_e64 s[0:1], 0, v67
	s_nop 1
	v_cndmask_b32_e64 v67, v84, v85, s[0:1]
	v_mul_f32_e32 v84, 0x37800000, v67
	v_cndmask_b32_e32 v67, v67, v84, vcc
	v_mov_b32_e32 v84, 0x260
	v_cmp_class_f32_e32 vcc, v66, v84
	s_nop 1
	v_cndmask_b32_e32 v66, v67, v66, vcc
	v_div_scale_f32 v67, s[0:1], v66, v66, s4
	v_rcp_f32_e32 v84, v67
	v_readlane_b32 s0, v254, 54
	v_readlane_b32 s1, v254, 55
	v_fma_f32 v85, -v67, v84, 1.0
	v_fmac_f32_e32 v84, v85, v84
	v_div_scale_f32 v85, vcc, s4, v66, s4
	v_mul_f32_e32 v86, v85, v84
	v_fma_f32 v87, -v67, v86, v85
	v_fmac_f32_e32 v86, v87, v84
	v_fma_f32 v67, -v67, v86, v85
	v_div_fmas_f32 v67, v67, v84, v86
	v_div_fixup_f32 v66, v67, v66, s4
	v_lshl_add_u64 v[82:83], s[0:1], 0, v[82:83]
	v_lshl_add_u64 v[82:83], v[82:83], 0, s[98:99]
	s_waitcnt vmcnt(0)
	v_mov_b32_e32 v67, v72
	s_nop 1
	v_permlane32_swap_b32_e32 v70, v67
	v_pk_mul_f32 v[50:51], v[50:51], v[66:67] op_sel_hi:[1,0]
	v_mov_b32_e32 v84, v73
	v_lshlrev_b32_e32 v72, 16, v70
	v_and_b32_e32 v73, 0xffff0000, v70
	s_nop 0
	v_pk_mul_f32 v[50:51], v[74:75], v[50:51]
	v_permlane32_swap_b32_e32 v71, v84
	v_pk_mul_f32 v[50:51], v[50:51], v[72:73]
	v_pk_mul_f32 v[52:53], v[52:53], v[66:67] op_sel_hi:[1,0]
	v_cvt_pk_bf16_f32 v70, v50, v51
	v_lshlrev_b32_e32 v50, 16, v71
	v_and_b32_e32 v51, 0xffff0000, v71
	v_pk_mul_f32 v[52:53], v[76:77], v[52:53]
	s_nop 0
	v_pk_mul_f32 v[50:51], v[52:53], v[50:51]
	v_pk_mul_f32 v[52:53], v[54:55], v[66:67] op_sel_hi:[1,0]
	v_cvt_pk_bf16_f32 v71, v50, v51
	v_lshlrev_b32_e32 v50, 16, v67
	v_and_b32_e32 v51, 0xffff0000, v67
	s_nop 0
	v_pk_mul_f32 v[52:53], v[78:79], v[52:53]
	s_nop 0
	v_pk_mul_f32 v[50:51], v[52:53], v[50:51]
	v_pk_mul_f32 v[52:53], v[56:57], v[66:67] op_sel_hi:[1,0]
	v_cvt_pk_bf16_f32 v72, v50, v51
	v_lshlrev_b32_e32 v50, 16, v84
	v_and_b32_e32 v51, 0xffff0000, v84
	v_pk_mul_f32 v[52:53], v[80:81], v[52:53]
	v_permlane32_swap_b32_e32 v70, v72
	v_pk_mul_f32 v[50:51], v[52:53], v[50:51]
	s_nop 0
	v_cvt_pk_bf16_f32 v73, v50, v51
	s_nop 1
	v_permlane32_swap_b32_e32 v71, v73
	v_lshl_add_u64 v[50:51], v[82:83], 0, v[0:1]
	global_store_dwordx4 v[50:51], v[70:73], off offset:1024
	s_nop 0
	v_mov_b32_e32 v67, v114
	s_nop 1
	v_permlane32_swap_b32_e32 v112, v67
	v_pk_mul_f32 v[56:57], v[58:59], v[66:67] op_sel_hi:[1,0]
	v_mov_b32_e32 v78, v115
	v_lshlrev_b32_e32 v114, 16, v112
	v_and_b32_e32 v115, 0xffff0000, v112
	s_nop 0
	v_pk_mul_f32 v[56:57], v[56:57], v[116:117]
	v_permlane32_swap_b32_e32 v113, v78
	v_pk_mul_f32 v[114:115], v[56:57], v[114:115]
	v_pk_mul_f32 v[56:57], v[60:61], v[66:67] op_sel_hi:[1,0]
	v_cvt_pk_bf16_f32 v112, v114, v115
	v_lshlrev_b32_e32 v114, 16, v113
	v_and_b32_e32 v115, 0xffff0000, v113
	v_pk_mul_f32 v[56:57], v[56:57], v[118:119]
	v_pk_mul_f32 v[58:59], v[64:65], v[66:67] op_sel_hi:[1,0]
	v_pk_mul_f32 v[114:115], v[56:57], v[114:115]
	v_pk_mul_f32 v[56:57], v[62:63], v[66:67] op_sel_hi:[1,0]
	v_cvt_pk_bf16_f32 v113, v114, v115
	v_lshlrev_b32_e32 v114, 16, v67
	v_and_b32_e32 v115, 0xffff0000, v67
	s_nop 0
	v_pk_mul_f32 v[56:57], v[56:57], v[120:121]
	v_pk_mul_f32 v[58:59], v[58:59], v[122:123]
	v_pk_mul_f32 v[114:115], v[56:57], v[114:115]
	v_lshlrev_b32_e32 v56, 16, v78
	v_and_b32_e32 v57, 0xffff0000, v78
	v_pk_mul_f32 v[56:57], v[58:59], v[56:57]
	v_cvt_pk_bf16_f32 v114, v114, v115
	v_cvt_pk_bf16_f32 v115, v56, v57
	s_nop 0
	v_permlane32_swap_b32_e32 v112, v114
	v_permlane32_swap_b32_e32 v113, v115
	global_store_dwordx4 v[50:51], v[112:115], off offset:1056
	v_pk_mul_f32 v[34:35], v[34:35], v[66:67] op_sel_hi:[1,0]
	v_pk_mul_f32 v[36:37], v[36:37], v[66:67] op_sel_hi:[1,0]
	v_pk_mul_f32 v[38:39], v[38:39], v[66:67] op_sel_hi:[1,0]
	v_pk_mul_f32 v[40:41], v[40:41], v[66:67] op_sel_hi:[1,0]
	v_pk_mul_f32 v[42:43], v[42:43], v[66:67] op_sel_hi:[1,0]
	v_pk_mul_f32 v[44:45], v[44:45], v[66:67] op_sel_hi:[1,0]
	v_pk_mul_f32 v[46:47], v[46:47], v[66:67] op_sel_hi:[1,0]
	v_pk_mul_f32 v[48:49], v[48:49], v[66:67] op_sel_hi:[1,0]
	v_pk_mul_f32 v[18:19], v[18:19], v[66:67] op_sel_hi:[1,0]
	v_pk_mul_f32 v[20:21], v[20:21], v[66:67] op_sel_hi:[1,0]
	v_pk_mul_f32 v[22:23], v[22:23], v[66:67] op_sel_hi:[1,0]
	v_pk_mul_f32 v[24:25], v[24:25], v[66:67] op_sel_hi:[1,0]
	v_pk_mul_f32 v[26:27], v[26:27], v[66:67] op_sel_hi:[1,0]
	v_pk_mul_f32 v[28:29], v[28:29], v[66:67] op_sel_hi:[1,0]
	v_pk_mul_f32 v[30:31], v[30:31], v[66:67] op_sel_hi:[1,0]
	v_pk_mul_f32 v[32:33], v[32:33], v[66:67] op_sel_hi:[1,0]
	v_pk_mul_f32 v[2:3], v[2:3], v[66:67] op_sel_hi:[1,0]
	v_pk_mul_f32 v[4:5], v[4:5], v[66:67] op_sel_hi:[1,0]
	v_pk_mul_f32 v[6:7], v[6:7], v[66:67] op_sel_hi:[1,0]
	v_pk_mul_f32 v[8:9], v[8:9], v[66:67] op_sel_hi:[1,0]
	v_pk_mul_f32 v[10:11], v[10:11], v[66:67] op_sel_hi:[1,0]
	v_pk_mul_f32 v[12:13], v[12:13], v[66:67] op_sel_hi:[1,0]
	v_pk_mul_f32 v[14:15], v[14:15], v[66:67] op_sel_hi:[1,0]
	v_pk_mul_f32 v[16:17], v[16:17], v[66:67] op_sel_hi:[1,0]
	s_nop 0
	v_mov_b32_e32 v64, v126
	v_mov_b32_e32 v65, v127
	s_nop 0
	v_permlane32_swap_b32_e32 v124, v64
	v_permlane32_swap_b32_e32 v125, v65
	s_nop 0
	v_pk_mul_f32 v[34:35], v[34:35], v[128:129]
	v_pk_mul_f32 v[36:37], v[36:37], v[130:131]
	s_nop 0
	v_pk_mul_f32 v[38:39], v[38:39], v[132:133]
	v_pk_mul_f32 v[40:41], v[40:41], v[134:135]
; DI unsigned cvtpk(float lo, float hi) { f32x2 v = {lo, hi}; bf16x2 b = __builtin_convertvector(v, bf16x2); return __builtin_bit_cast(unsigned, b); }
; DI float bf_lo(unsigned w) { return __uint_as_float(w << 16); }
; DI float bf_hi(unsigned w) { return __uint_as_float(w & 0xffff0000u); }
; DI void swz_in(u32x4 t, u32x2& g0, u32x2& g1) { auto r0 = __builtin_amdgcn_permlane32_swap(t.x, t.z, false, false); auto r1 = __builtin_amdgcn_permlane32_swap(t.y, t.w, false, false); g0.x = r0[0]; g0.y = r1[0]; g1.x = r0[1]; g1.y = r1[1]; }
; DI u32x4 swz_out(u32x2 w0, u32x2 w1) { auto r0 = __builtin_amdgcn_permlane32_swap(w0.x, w1.x, false, false); auto r1 = __builtin_amdgcn_permlane32_swap(w0.y, w1.y, false, false); u32x4 o; o.x = r0[0]; o.y = r1[0]; o.z = r0[1]; o.w = r1[1]; return o; }
; DI void df_unit(LAS char* lds, int b, int h, int qb, const bf16_t* __restrict__ Q, const bf16_t* __restrict__ K, const bf16_t* __restrict__ VT, const bf16_t* __restrict__ G, bf16_t* __restrict__ MIX,
;                 float lam, float Mb  , const float* __restrict__ subg) {
;     ...
;         for (int db = 0; db < 4; ++db)
; #pragma unroll
;             for (int gp = 0; gp < 2; ++gp) { const int dc = 32 * db + 16 * gp + 8 * hi2, d0 = 32 * db + 16 * gp + 4 * hi2, d1 = d0 + 8; const int r0 = 8 * gp, r1 = 8 * gp + 4;
;                 u32x2 g0, g1; swz_in(*(const u32x4*)(G + trow * 512 + h * 128 + dc), g0, g1);
;                 const f32x4 s0 = *(const f32x4*)(subg + d0), s1 = *(const f32x4*)(subg + d1);
;                 u32x2 w0, w1;
;                 w0.x = cvtpk(O[db][r0] * rs * s0[0] * bf_lo(g0.x), O[db][r0 + 1] * rs * s0[1] * bf_hi(g0.x)); w0.y = cvtpk(O[db][r0 + 2] * rs * s0[2] * bf_lo(g0.y), O[db][r0 + 3] * rs * s0[3] * bf_hi(g0.y));
;                 w1.x = cvtpk(O[db][r1] * rs * s1[0] * bf_lo(g1.x), O[db][r1 + 1] * rs * s1[1] * bf_hi(g1.x)); w1.y = cvtpk(O[db][r1 + 2] * rs * s1[2] * bf_lo(g1.y), O[db][r1 + 3] * rs * s1[3] * bf_hi(g1.y));
;                 *(u32x4*)(MIX + trow * 1024 + 512 + h * 128 + dc) = swz_out(w0, w1); asm volatile("" ::: "memory"); }
	v_lshlrev_b32_e32 v126, 16, v124
	v_and_b32_e32 v127, 0xffff0000, v124
	v_lshlrev_b32_e32 v124, 16, v125
	v_and_b32_e32 v125, 0xffff0000, v125
	v_lshlrev_b32_e32 v128, 16, v64
	v_and_b32_e32 v129, 0xffff0000, v64
	v_lshlrev_b32_e32 v130, 16, v65
	v_and_b32_e32 v131, 0xffff0000, v65
	v_pk_mul_f32 v[34:35], v[34:35], v[126:127]
	v_pk_mul_f32 v[36:37], v[36:37], v[124:125]
	v_pk_mul_f32 v[38:39], v[38:39], v[128:129]
	v_pk_mul_f32 v[40:41], v[40:41], v[130:131]
	v_cvt_pk_bf16_f32 v34, v34, v35
	v_cvt_pk_bf16_f32 v35, v36, v37
	v_cvt_pk_bf16_f32 v36, v38, v39
	v_cvt_pk_bf16_f32 v37, v40, v41
	s_nop 0
	v_permlane32_swap_b32_e32 v34, v36
	v_permlane32_swap_b32_e32 v35, v37
	global_store_dwordx4 v[50:51], v[34:37], off offset:1088
	s_nop 0
	v_mov_b32_e32 v56, v138
	v_mov_b32_e32 v57, v139
	s_nop 0
	v_permlane32_swap_b32_e32 v136, v56
	v_permlane32_swap_b32_e32 v137, v57
	s_nop 0
	v_pk_mul_f32 v[138:139], v[42:43], v[140:141]
	v_pk_mul_f32 v[140:141], v[44:45], v[142:143]
	s_nop 0
	v_pk_mul_f32 v[142:143], v[46:47], v[144:145]
	v_pk_mul_f32 v[42:43], v[48:49], v[146:147]
	v_lshlrev_b32_e32 v44, 16, v136
	v_and_b32_e32 v45, 0xffff0000, v136
	v_lshlrev_b32_e32 v136, 16, v137
	v_and_b32_e32 v137, 0xffff0000, v137
	v_lshlrev_b32_e32 v46, 16, v56
	v_and_b32_e32 v47, 0xffff0000, v56
	v_lshlrev_b32_e32 v48, 16, v57
	v_and_b32_e32 v49, 0xffff0000, v57
	v_pk_mul_f32 v[138:139], v[138:139], v[44:45]
	v_pk_mul_f32 v[140:141], v[140:141], v[136:137]
	v_pk_mul_f32 v[142:143], v[142:143], v[46:47]
	v_pk_mul_f32 v[42:43], v[42:43], v[48:49]
	v_cvt_pk_bf16_f32 v136, v138, v139
	v_cvt_pk_bf16_f32 v137, v140, v141
	v_cvt_pk_bf16_f32 v138, v142, v143
	v_cvt_pk_bf16_f32 v139, v42, v43
	s_nop 0
	v_permlane32_swap_b32_e32 v136, v138
	v_permlane32_swap_b32_e32 v137, v139
	global_store_dwordx4 v[50:51], v[136:139], off offset:1120
	s_nop 0
	v_mov_b32_e32 v46, v150
	v_mov_b32_e32 v47, v151
	s_nop 0
	v_permlane32_swap_b32_e32 v148, v46
	v_permlane32_swap_b32_e32 v149, v47
	s_nop 0
	v_pk_mul_f32 v[18:19], v[18:19], v[152:153]
	v_pk_mul_f32 v[20:21], v[20:21], v[154:155]
	s_nop 0
	v_pk_mul_f32 v[22:23], v[22:23], v[156:157]
	v_pk_mul_f32 v[24:25], v[24:25], v[158:159]
	v_lshlrev_b32_e32 v150, 16, v148
	v_and_b32_e32 v151, 0xffff0000, v148
	v_lshlrev_b32_e32 v148, 16, v149
	v_and_b32_e32 v149, 0xffff0000, v149
	v_lshlrev_b32_e32 v152, 16, v46
	v_and_b32_e32 v153, 0xffff0000, v46
	v_lshlrev_b32_e32 v154, 16, v47
	v_and_b32_e32 v155, 0xffff0000, v47
	v_pk_mul_f32 v[18:19], v[18:19], v[150:151]
	v_pk_mul_f32 v[20:21], v[20:21], v[148:149]
	v_pk_mul_f32 v[22:23], v[22:23], v[152:153]
	v_pk_mul_f32 v[24:25], v[24:25], v[154:155]
	v_cvt_pk_bf16_f32 v18, v18, v19
	v_cvt_pk_bf16_f32 v19, v20, v21
	v_cvt_pk_bf16_f32 v20, v22, v23
	v_cvt_pk_bf16_f32 v21, v24, v25
	s_nop 0
	v_permlane32_swap_b32_e32 v18, v20
	v_permlane32_swap_b32_e32 v19, v21
	global_store_dwordx4 v[50:51], v[18:21], off offset:1152
	s_nop 0
	v_mov_b32_e32 v38, v162
	v_mov_b32_e32 v39, v163
	s_nop 0
	v_permlane32_swap_b32_e32 v160, v38
	v_permlane32_swap_b32_e32 v161, v39
	s_nop 0
	v_pk_mul_f32 v[162:163], v[26:27], v[164:165]
	v_pk_mul_f32 v[164:165], v[28:29], v[166:167]
	s_nop 0
	v_pk_mul_f32 v[166:167], v[30:31], v[168:169]
	v_pk_mul_f32 v[26:27], v[32:33], v[170:171]
	v_lshlrev_b32_e32 v28, 16, v160
	v_and_b32_e32 v29, 0xffff0000, v160
	v_lshlrev_b32_e32 v160, 16, v161
	v_and_b32_e32 v161, 0xffff0000, v161
	v_lshlrev_b32_e32 v30, 16, v38
	v_and_b32_e32 v31, 0xffff0000, v38
	v_lshlrev_b32_e32 v32, 16, v39
	v_and_b32_e32 v33, 0xffff0000, v39
	v_pk_mul_f32 v[162:163], v[162:163], v[28:29]
	v_pk_mul_f32 v[164:165], v[164:165], v[160:161]
	v_pk_mul_f32 v[166:167], v[166:167], v[30:31]
	v_pk_mul_f32 v[26:27], v[26:27], v[32:33]
	v_cvt_pk_bf16_f32 v160, v162, v163
	v_cvt_pk_bf16_f32 v161, v164, v165
	v_cvt_pk_bf16_f32 v162, v166, v167
	v_cvt_pk_bf16_f32 v163, v26, v27
	s_nop 0
	v_permlane32_swap_b32_e32 v160, v162
	v_permlane32_swap_b32_e32 v161, v163
	global_store_dwordx4 v[50:51], v[160:163], off offset:1184
	s_nop 0
	v_mov_b32_e32 v30, v174
	v_mov_b32_e32 v31, v175
	s_nop 0
	v_permlane32_swap_b32_e32 v172, v30
	v_permlane32_swap_b32_e32 v173, v31
	s_nop 0
	v_pk_mul_f32 v[2:3], v[2:3], v[176:177]
	v_pk_mul_f32 v[4:5], v[4:5], v[178:179]
	s_nop 0
	v_pk_mul_f32 v[6:7], v[6:7], v[180:181]
	v_pk_mul_f32 v[8:9], v[8:9], v[182:183]
	v_lshlrev_b32_e32 v174, 16, v172
	v_and_b32_e32 v175, 0xffff0000, v172
	v_lshlrev_b32_e32 v172, 16, v173
	v_and_b32_e32 v173, 0xffff0000, v173
	v_lshlrev_b32_e32 v176, 16, v30
	v_and_b32_e32 v177, 0xffff0000, v30
	v_lshlrev_b32_e32 v178, 16, v31
	v_and_b32_e32 v179, 0xffff0000, v31
	v_pk_mul_f32 v[2:3], v[2:3], v[174:175]
	v_pk_mul_f32 v[4:5], v[4:5], v[172:173]
	v_pk_mul_f32 v[6:7], v[6:7], v[176:177]
	v_pk_mul_f32 v[8:9], v[8:9], v[178:179]
	v_cvt_pk_bf16_f32 v2, v2, v3
	v_cvt_pk_bf16_f32 v3, v4, v5
	v_cvt_pk_bf16_f32 v4, v6, v7
	v_cvt_pk_bf16_f32 v5, v8, v9
	s_nop 0
	v_permlane32_swap_b32_e32 v2, v4
	v_permlane32_swap_b32_e32 v3, v5
	global_store_dwordx4 v[50:51], v[2:5], off offset:1216
	s_nop 0
	v_mov_b32_e32 v0, v186
	v_mov_b32_e32 v22, v187
	s_nop 0
	v_permlane32_swap_b32_e32 v184, v0
	v_permlane32_swap_b32_e32 v185, v22
	s_nop 0
	v_pk_mul_f32 v[186:187], v[10:11], v[188:189]
	v_pk_mul_f32 v[188:189], v[12:13], v[190:191]
	s_nop 0
	v_pk_mul_f32 v[190:191], v[14:15], v[192:193]
	v_pk_mul_f32 v[10:11], v[16:17], v[194:195]
	v_lshlrev_b32_e32 v12, 16, v184
	v_and_b32_e32 v13, 0xffff0000, v184
	v_lshlrev_b32_e32 v184, 16, v185
	v_and_b32_e32 v185, 0xffff0000, v185
	v_lshlrev_b32_e32 v14, 16, v0
	v_and_b32_e32 v15, 0xffff0000, v0
	v_lshlrev_b32_e32 v16, 16, v22
	v_and_b32_e32 v17, 0xffff0000, v22
	v_pk_mul_f32 v[186:187], v[186:187], v[12:13]
	v_pk_mul_f32 v[188:189], v[188:189], v[184:185]
	v_pk_mul_f32 v[190:191], v[190:191], v[14:15]
	v_pk_mul_f32 v[10:11], v[10:11], v[16:17]
	v_cvt_pk_bf16_f32 v184, v186, v187
	v_cvt_pk_bf16_f32 v185, v188, v189
	v_cvt_pk_bf16_f32 v186, v190, v191
	v_cvt_pk_bf16_f32 v187, v10, v11
	s_nop 0
	v_permlane32_swap_b32_e32 v184, v186
	v_permlane32_swap_b32_e32 v185, v187
	global_store_dwordx4 v[50:51], v[184:187], off offset:1248
	s_branch .LBB0_345

; #define LAS __attribute__((address_space(3)))
; #define WAIT_BAR0() asm volatile("s_waitcnt vmcnt(0) lgkmcnt(0)\n\ts_barrier" ::: "memory")
; #define SB_DMA(T, st) do { const unsigned base_ = lds0 + (st) * 16384 + wid * 1024; glds16(ksrc + (size_t)(T) * 64 * 512, RFL(base_)); glds16(vsrc + (size_t)(T) * 4096, RFL(base_ + 8192)); } while (0)
; DI void sb_unit(LAS char* lds, int b, int h, int qb, const bf16_t* __restrict__ Q, const bf16_t* __restrict__ K, const bf16_t* __restrict__ VT, const bf16_t* __restrict__ G, bf16_t* __restrict__ MIX) {
;     ...
;     for (int T = nt - 1, it = 0; T >= 0; --T, ++it) {
;         WAIT_BAR0();
;         if (it > 0) { volatile LAS int* fl = flags + ((it & 1) ^ 1) * 8; const int all = fl[0] & fl[1] & fl[2] & fl[3] & fl[4] & fl[5] & fl[6] & fl[7]; if (all) break; }
;         if (T > 0) SB_DMA(T - 1, (it + 1) & 1);
;         const LAS char* Kt = lds + (it & 1) * 16384; const LAS char* Vt = Kt + 8192;
;         const int kv0 = 64 * T;
;     ...
;         if (lane == 0) flags[(it & 1) * 8 + wid] = done;
.LBB0_414:
	s_lshl_b32 s0, s27, 2
	v_and_b32_e32 v35, 63, v35
	s_add_i32 s27, s0, 0
	v_cmp_eq_u32_e64 s[36:37], 0, v35
	s_add_i32 s27, s27, 0x20000
	s_and_saveexec_b64 s[0:1], s[36:37]
	v_mov_b32_e32 v35, s27
	ds_write_b32 v35, v36
	s_or_b64 exec, exec, s[0:1]
	s_lshl_b32 s0, s38, 6
	s_add_i32 s98, s38, -2
	s_lshr_b32 s46, s25, 11
	s_lshl_b32 s46, s46, 6
	s_add_i32 s39, s0, s46
	s_add_i32 s39, s39, 0xffffff00
	s_mov_b32 s38, 1
	s_movk_i32 s40, 0x4000
	s_mov_b32 s41, 8
	s_branch .LBB0_418

; #define LAS __attribute__((address_space(3)))
; #define MFMA32(a, b, c) __builtin_amdgcn_mfma_f32_32x32x16_bf16((a), (b), (c), 0, 0, 0)
; #define SB_DMA(T, st) do { const unsigned base_ = lds0 + (st) * 16384 + wid * 1024; glds16(ksrc + (size_t)(T) * 64 * 512, RFL(base_)); glds16(vsrc + (size_t)(T) * 4096, RFL(base_ + 8192)); } while (0)
; DI void sb_unit(LAS char* lds, int b, int h, int qb, const bf16_t* __restrict__ Q, const bf16_t* __restrict__ K, const bf16_t* __restrict__ VT, const bf16_t* __restrict__ G, bf16_t* __restrict__ MIX) {
;     ...
;         if (it > 0) { volatile LAS int* fl = flags + ((it & 1) ^ 1) * 8; const int all = fl[0] & fl[1] & fl[2] & fl[3] & fl[4] & fl[5] & fl[6] & fl[7]; if (all) break; }
;         if (T > 0) SB_DMA(T - 1, (it + 1) & 1);
;         const LAS char* Kt = lds + (it & 1) * 16384; const LAS char* Vt = Kt + 8192;
;         const int kv0 = 64 * T;
;         if (kv0 < qw0 + 31 && !done) {
;             f32x16 p0 = splat16(0.f), p1 = splat16(0.f);
; #pragma unroll
;             for (int d0 = 0; d0 < 4; ++d0) { const bf16x8 k0 = ldsv(Kt + off128(r32, 2 * d0 + hi)), k1 = ldsv(Kt + off128(32 + r32, 2 * d0 + hi)); p0 = MFMA32(k0, qf[d0], p0); p1 = MFMA32(k1, qf[d0], p1); }
.LBB0_420:
	s_cmp_lt_i32 s98, 3
	s_cbranch_scc1 .LBB0_422
	s_add_i32 s46, s98, -3
	s_mov_b32 s47, 0
	s_and_b32 s0, s46, 7
	s_lshl_b32 s0, s0, 14
	s_add_i32 s4, s25, s0
	s_lshl_b64 s[0:1], s[46:47], 16
	v_lshl_add_u64 v[38:39], v[96:97], 0, s[0:1]
	s_mov_b32 s0, m0
	s_mov_b32 m0, s4
	s_nop 0
	global_load_lds_dwordx4 v[38:39], off
	s_mov_b32 m0, s0
	s_lshl_b64 s[0:1], s[46:47], 13
	v_lshl_add_u64 v[38:39], v[98:99], 0, s[0:1]
	s_add_i32 s0, s4, 0x2000
	s_mov_b32 s1, m0
	s_mov_b32 m0, s0
	s_nop 0
	global_load_lds_dwordx4 v[38:39], off
	s_mov_b32 m0, s1
.LBB0_422:
	s_and_b32 s42, s38, 1
	s_cmp_lt_i32 s39, 0
	s_cbranch_scc1 .LBB0_424
	s_cmp_ge_i32 s39, s26
	s_cselect_b64 s[0:1], -1, 0
	v_cmp_ne_u32_e32 vcc, 0, v36
	s_or_b64 s[0:1], s[0:1], vcc
	s_and_b64 vcc, exec, s[0:1]
	s_cbranch_vccnz .LBB0_424
	s_lshr_b32 s0, s39, 6
	s_and_b32 s0, s0, 7
	s_lshl_b32 s0, s0, 14
	s_add_i32 s43, s0, 0
	v_add_u32_e32 v35, s43, v103
	v_add_u32_e32 v40, v35, v104
	ds_read_b128 v[36:39], v40
	ds_read_b128 v[40:43], v40 offset:4096
	v_add_u32_e32 v112, v35, v105
	ds_read_b128 v[108:111], v112
	ds_read_b128 v[112:115], v112 offset:4096
	s_add_i32 s0, s39, 63
	s_waitcnt lgkmcnt(3)
	v_mfma_f32_32x32x16_bf16 v[52:67], v[36:39], v[68:71], 0
	s_cmp_lt_i32 s0, s24
	s_cselect_b64 s[0:1], -1, 0
	v_readlane_b32 s4, v254, 48
	v_readlane_b32 s6, v254, 50
	v_readlane_b32 s7, v254, 51
	v_readlane_b32 s5, v254, 49
	s_mov_b32 s6, s4
	s_waitcnt lgkmcnt(2)
	v_mfma_f32_32x32x16_bf16 v[36:51], v[40:43], v[68:71], 0
	s_mov_b32 s7, s4
	s_mov_b32 s5, s4
	s_waitcnt lgkmcnt(1)
	v_mfma_f32_32x32x16_bf16 v[52:67], v[108:111], v[72:75], v[52:67]
	s_waitcnt lgkmcnt(0)
	v_mfma_f32_32x32x16_bf16 v[36:51], v[112:115], v[72:75], v[36:51]
	v_add_u32_e32 v112, v35, v106
	ds_read_b128 v[108:111], v112
	ds_read_b128 v[112:115], v112 offset:4096
	v_add_u32_e32 v35, v35, v107
	s_waitcnt lgkmcnt(1)
	v_mfma_f32_32x32x16_bf16 v[52:67], v[108:111], v[76:79], v[52:67]
	s_waitcnt lgkmcnt(0)
	v_mfma_f32_32x32x16_bf16 v[36:51], v[112:115], v[76:79], v[36:51]
	ds_read_b128 v[108:111], v35
	ds_read_b128 v[112:115], v35 offset:4096
	v_add_u32_e32 v35, s39, v102
	v_add_u32_e32 v133, 24, v35
	v_add_u32_e32 v138, 58, v35
	s_waitcnt lgkmcnt(1)
	v_mfma_f32_32x32x16_bf16 v[52:67], v[108:111], v[80:83], v[52:67]
	v_add_u32_e32 v110, 32, v35
	s_waitcnt lgkmcnt(0)
; DI int crow(int r, int hi) { return (r & 3) + 8 * (r >> 2) + 4 * hi; }
; DI float ex2(float x) { return __builtin_amdgcn_exp2f(x); }
; DI float lg2(float x) { return __builtin_amdgcn_logf(x); }
; template <int S> DI bf16x8 pack8(const f32x16& x) { u32x4 p; p[0] = cvtpk(x[8 * S], x[8 * S + 1]); p[1] = cvtpk(x[8 * S + 2], x[8 * S + 3]); p[2] = cvtpk(x[8 * S + 4], x[8 * S + 5]); p[3] = cvtpk(x[8 * S + 6], x[8 * S + 7]); return __builtin_bit_cast(bf16x8, p); }
; DI void sb_unit(LAS char* lds, int b, int h, int qb, const bf16_t* __restrict__ Q, const bf16_t* __restrict__ K, const bf16_t* __restrict__ VT, const bf16_t* __restrict__ G, bf16_t* __restrict__ MIX) {
;     ...
;             for (int r = 0; r < 16; ++r) {
;                 { const float z = p0[r]; const float lg = (z > 30.f) ? z : lg2(1.0f + ex2(z)); const bool valid = !diag || (kv0 + crow(r, hi) < tq); L0[r] = valid ? -lg : 0.f; p0[r] = valid ? (z - lg) : -1e30f; }
;                 { const float z = p1[r]; const float lg = (z > 30.f) ? z : lg2(1.0f + ex2(z)); const bool valid = !diag || (kv0 + 32 + crow(r, hi) < tq); L1[r] = valid ? -lg : 0.f; p1[r] = valid ? (z - lg) : -1e30f; }
;             }
;             const bf16x8 Lh0 = pack8<0>(L0), Lh1 = pack8<1>(L0), Lh2 = pack8<0>(L1), Lh3 = pack8<1>(L1);
	v_mfma_f32_32x32x16_bf16 v[36:51], v[112:115], v[80:83], v[36:51]
	s_nop 8
	v_exp_f32_e32 v160, v52
	v_exp_f32_e32 v161, v53
	v_exp_f32_e32 v162, v54
	v_exp_f32_e32 v163, v55
	v_exp_f32_e32 v164, v56
	v_exp_f32_e32 v165, v57
	v_exp_f32_e32 v166, v58
	v_exp_f32_e32 v167, v59
	v_exp_f32_e32 v168, v60
	v_exp_f32_e32 v169, v61
	v_exp_f32_e32 v170, v62
	v_exp_f32_e32 v171, v63
	v_exp_f32_e32 v172, v64
	v_exp_f32_e32 v173, v65
	v_exp_f32_e32 v174, v66
	v_exp_f32_e32 v175, v67
	v_exp_f32_e32 v176, v36
	v_exp_f32_e32 v177, v37
	v_exp_f32_e32 v178, v38
	v_exp_f32_e32 v179, v39
	v_exp_f32_e32 v180, v40
	v_exp_f32_e32 v181, v41
	v_exp_f32_e32 v182, v42
	v_exp_f32_e32 v183, v43
	v_exp_f32_e32 v184, v44
	v_exp_f32_e32 v185, v45
	v_exp_f32_e32 v186, v46
	v_exp_f32_e32 v187, v47
	v_exp_f32_e32 v188, v48
	v_exp_f32_e32 v189, v49
	v_exp_f32_e32 v190, v50
	v_exp_f32_e32 v191, v51
	v_add_f32_e32 v160, 1.0, v160
	v_add_f32_e32 v161, 1.0, v161
	v_add_f32_e32 v162, 1.0, v162
	v_add_f32_e32 v163, 1.0, v163
	v_add_f32_e32 v164, 1.0, v164
	v_add_f32_e32 v165, 1.0, v165
	v_add_f32_e32 v166, 1.0, v166
	v_add_f32_e32 v167, 1.0, v167
	v_add_f32_e32 v168, 1.0, v168
	v_add_f32_e32 v169, 1.0, v169
	v_add_f32_e32 v170, 1.0, v170
	v_add_f32_e32 v171, 1.0, v171
	v_add_f32_e32 v172, 1.0, v172
	v_add_f32_e32 v173, 1.0, v173
	v_add_f32_e32 v174, 1.0, v174
	v_add_f32_e32 v175, 1.0, v175
	v_add_f32_e32 v176, 1.0, v176
	v_add_f32_e32 v177, 1.0, v177
	v_add_f32_e32 v178, 1.0, v178
	v_add_f32_e32 v179, 1.0, v179
	v_add_f32_e32 v180, 1.0, v180
	v_add_f32_e32 v181, 1.0, v181
	v_add_f32_e32 v182, 1.0, v182
	v_add_f32_e32 v183, 1.0, v183
	v_add_f32_e32 v184, 1.0, v184
	v_add_f32_e32 v185, 1.0, v185
	v_add_f32_e32 v186, 1.0, v186
	v_add_f32_e32 v187, 1.0, v187
	v_add_f32_e32 v188, 1.0, v188
	v_add_f32_e32 v189, 1.0, v189
	v_add_f32_e32 v190, 1.0, v190
	v_add_f32_e32 v191, 1.0, v191
	v_log_f32_e32 v160, v160
	v_log_f32_e32 v161, v161
	v_log_f32_e32 v162, v162
	v_log_f32_e32 v163, v163
	v_log_f32_e32 v164, v164
	v_log_f32_e32 v165, v165
	v_log_f32_e32 v166, v166
	v_log_f32_e32 v167, v167
	v_log_f32_e32 v168, v168
	v_log_f32_e32 v169, v169
	v_log_f32_e32 v170, v170
	v_log_f32_e32 v171, v171
	v_log_f32_e32 v172, v172
	v_log_f32_e32 v173, v173
	v_log_f32_e32 v174, v174
	v_log_f32_e32 v175, v175
	v_log_f32_e32 v176, v176
	v_log_f32_e32 v177, v177
	v_log_f32_e32 v178, v178
	v_log_f32_e32 v179, v179
	v_log_f32_e32 v180, v180
	v_log_f32_e32 v181, v181
	v_log_f32_e32 v182, v182
	v_log_f32_e32 v183, v183
	v_log_f32_e32 v184, v184
	v_log_f32_e32 v185, v185
	v_log_f32_e32 v186, v186
	v_log_f32_e32 v187, v187
	v_log_f32_e32 v188, v188
	v_log_f32_e32 v189, v189
	v_log_f32_e32 v190, v190
	v_log_f32_e32 v191, v191
	v_cmp_lt_f32_e64 s[52:53], s22, v52
	v_cmp_lt_f32_e64 s[54:55], s22, v53
	v_cmp_lt_f32_e64 s[56:57], s22, v54
	v_cmp_lt_f32_e64 s[58:59], s22, v55
	v_cmp_lt_f32_e64 s[60:61], s22, v56
	v_cmp_lt_f32_e64 s[62:63], s22, v57
	v_cmp_lt_f32_e64 s[64:65], s22, v58
	v_cmp_lt_f32_e64 s[66:67], s22, v59
	v_cmp_lt_f32_e64 s[68:69], s22, v60
	v_cmp_lt_f32_e64 s[70:71], s22, v61
	v_cndmask_b32_e64 v160, v160, v52, s[52:53]
	v_cndmask_b32_e64 v161, v161, v53, s[54:55]
	v_cndmask_b32_e64 v162, v162, v54, s[56:57]
	v_cndmask_b32_e64 v163, v163, v55, s[58:59]
	v_cndmask_b32_e64 v164, v164, v56, s[60:61]
	v_cndmask_b32_e64 v165, v165, v57, s[62:63]
	v_cndmask_b32_e64 v166, v166, v58, s[64:65]
	v_cndmask_b32_e64 v167, v167, v59, s[66:67]
	v_cndmask_b32_e64 v168, v168, v60, s[68:69]
	v_cndmask_b32_e64 v169, v169, v61, s[70:71]
	v_cmp_lt_f32_e64 s[52:53], s22, v62
	v_cmp_lt_f32_e64 s[54:55], s22, v63
	v_cmp_lt_f32_e64 s[56:57], s22, v64
	v_cmp_lt_f32_e64 s[58:59], s22, v65
	v_cmp_lt_f32_e64 s[60:61], s22, v66
	v_cmp_lt_f32_e64 s[62:63], s22, v67
	v_cmp_lt_f32_e64 s[64:65], s22, v36
	v_cmp_lt_f32_e64 s[66:67], s22, v37
	v_cmp_lt_f32_e64 s[68:69], s22, v38
	v_cmp_lt_f32_e64 s[70:71], s22, v39
	v_cndmask_b32_e64 v170, v170, v62, s[52:53]
	v_cndmask_b32_e64 v171, v171, v63, s[54:55]
	v_cndmask_b32_e64 v172, v172, v64, s[56:57]
	v_cndmask_b32_e64 v173, v173, v65, s[58:59]
	v_cndmask_b32_e64 v174, v174, v66, s[60:61]
	v_cndmask_b32_e64 v175, v175, v67, s[62:63]
	v_cndmask_b32_e64 v176, v176, v36, s[64:65]
	v_cndmask_b32_e64 v177, v177, v37, s[66:67]
	v_cndmask_b32_e64 v178, v178, v38, s[68:69]
	v_cndmask_b32_e64 v179, v179, v39, s[70:71]
	v_cmp_lt_f32_e64 s[52:53], s22, v40
	v_cmp_lt_f32_e64 s[54:55], s22, v41
	v_cmp_lt_f32_e64 s[56:57], s22, v42
	v_cmp_lt_f32_e64 s[58:59], s22, v43
	v_cmp_lt_f32_e64 s[60:61], s22, v44
	v_cmp_lt_f32_e64 s[62:63], s22, v45
	v_cmp_lt_f32_e64 s[64:65], s22, v46
	v_cmp_lt_f32_e64 s[66:67], s22, v47
	v_cmp_lt_f32_e64 s[68:69], s22, v48
	v_cmp_lt_f32_e64 s[70:71], s22, v49
	v_cndmask_b32_e64 v180, v180, v40, s[52:53]
	v_cndmask_b32_e64 v181, v181, v41, s[54:55]
	v_cndmask_b32_e64 v182, v182, v42, s[56:57]
	v_cndmask_b32_e64 v183, v183, v43, s[58:59]
	v_cndmask_b32_e64 v184, v184, v44, s[60:61]
	v_cndmask_b32_e64 v185, v185, v45, s[62:63]
	v_cndmask_b32_e64 v186, v186, v46, s[64:65]
	v_cndmask_b32_e64 v187, v187, v47, s[66:67]
	v_cndmask_b32_e64 v188, v188, v48, s[68:69]
	v_cndmask_b32_e64 v189, v189, v49, s[70:71]
	v_cmp_lt_f32_e64 s[52:53], s22, v50
	v_cmp_lt_f32_e64 s[54:55], s22, v51
	s_nop 1
	v_cndmask_b32_e64 v190, v190, v50, s[52:53]
	v_cndmask_b32_e64 v191, v191, v51, s[54:55]
	s_and_b64 vcc, exec, s[0:1]
	s_cbranch_vccz .Lsb_sp_diag
	v_sub_f32_e32 v109, 0, v160
	v_cvt_pk_bf16_f32 v138, -v160, -v161
	v_cvt_pk_bf16_f32 v139, -v162, -v163
	v_cvt_pk_bf16_f32 v140, -v164, -v165
	v_cvt_pk_bf16_f32 v141, -v166, -v167
	v_cvt_pk_bf16_f32 v142, -v168, -v169
	v_cvt_pk_bf16_f32 v143, -v170, -v171
	v_cvt_pk_bf16_f32 v144, -v172, -v173
	v_cvt_pk_bf16_f32 v145, -v174, -v175
	v_cvt_pk_bf16_f32 v146, -v176, -v177
	v_cvt_pk_bf16_f32 v147, -v178, -v179
	v_cvt_pk_bf16_f32 v148, -v180, -v181
	v_cvt_pk_bf16_f32 v149, -v182, -v183
	v_cvt_pk_bf16_f32 v150, -v184, -v185
	v_cvt_pk_bf16_f32 v151, -v186, -v187
	v_cvt_pk_bf16_f32 v152, -v188, -v189
	v_cvt_pk_bf16_f32 v153, -v190, -v191
	v_sub_f32_e32 v108, v52, v160
	v_sub_f32_e32 v111, v53, v161
	v_sub_f32_e32 v113, v54, v162
	v_sub_f32_e32 v115, v55, v163
	v_sub_f32_e32 v117, v56, v164
	v_sub_f32_e32 v119, v57, v165
	v_sub_f32_e32 v121, v58, v166
	v_sub_f32_e32 v123, v59, v167
	v_sub_f32_e32 v125, v60, v168
	v_sub_f32_e32 v127, v61, v169
	v_sub_f32_e32 v129, v62, v170
	v_sub_f32_e32 v131, v63, v171
	v_sub_f32_e32 v133, v64, v172
	v_sub_f32_e32 v135, v65, v173
	v_sub_f32_e32 v66, v66, v174
	v_sub_f32_e32 v155, v67, v175
	v_sub_f32_e32 v110, v36, v176
	v_sub_f32_e32 v112, v37, v177
	v_sub_f32_e32 v114, v38, v178
	v_sub_f32_e32 v116, v39, v179
	v_sub_f32_e32 v118, v40, v180
	v_sub_f32_e32 v120, v41, v181
	v_sub_f32_e32 v122, v42, v182
	v_sub_f32_e32 v124, v43, v183
	v_sub_f32_e32 v126, v44, v184
	v_sub_f32_e32 v128, v45, v185
	v_sub_f32_e32 v130, v46, v186
	v_sub_f32_e32 v132, v47, v187
	v_sub_f32_e32 v134, v48, v188
	v_sub_f32_e32 v136, v49, v189
	v_sub_f32_e32 v154, v50, v190
	v_sub_f32_e32 v156, v51, v191
	s_branch .Lsb_sp_join
